# GEMM phases: wave priority raised (s_setprio 3) during the load segment (ds_read + LDS-DMA issue) and lowered during the MFMA block - the inverse of the source hints
# speedup vs baseline: 1.0076x; 1.0056x over previous
.LBB0_574:
	s_cmp_gt_u32 s63, 29
	s_cselect_b64 s[46:47], -1, 0
	ds_read_b128 v[160:163], v156
	ds_read_b128 v[164:167], v156 offset:1024
	ds_read_b128 v[168:171], v156 offset:2048
	ds_read_b128 v[172:175], v156 offset:3072
	ds_read_b128 v[176:179], v157
	ds_read_b128 v[180:183], v157 offset:1024
	ds_read_b128 v[184:187], v157 offset:2048
	ds_read_b128 v[188:191], v157 offset:3072
	s_and_b64 vcc, s[46:47], exec
	s_cselect_b32 s42, 0xffffffe2, 2
	s_add_i32 s46, s42, s63
	s_ashr_i32 s47, s46, 31
	s_lshl_b64 s[46:47], s[46:47], 7
	s_add_u32 s42, s50, s46
	s_addc_u32 s43, s51, s47
	s_add_u32 s46, s34, s46
	s_addc_u32 s47, s35, s47
	s_cmp_eq_u32 s63, 30
	s_cselect_b32 s53, s25, s43
	s_cselect_b32 s52, s61, s42
	s_cselect_b32 s47, s23, s47
	s_cselect_b32 s46, s62, s46
	s_add_i32 m0, s31, 0xc000
	ds_read_b128 v[192:195], v158
	ds_read_b128 v[196:199], v158 offset:1024
	ds_read_b128 v[200:203], v158 offset:2048
	ds_read_b128 v[204:207], v158 offset:3072
	ds_read_b128 v[208:211], v158 offset:4096
	ds_read_b128 v[212:215], v158 offset:5120
	ds_read_b128 v[216:219], v158 offset:6144
	ds_read_b128 v[220:223], v158 offset:7168
	global_load_lds_dwordx4 v[144:145], off
	s_add_i32 m0, s31, 0xe000
	s_nop 0
	global_load_lds_dwordx4 v[146:147], off
	s_waitcnt vmcnt(8)
	s_waitcnt lgkmcnt(0)
	s_barrier
	s_setprio 0
	s_waitcnt lgkmcnt(0)
	v_mfma_f32_16x16x32_bf16 v[124:127], v[160:163], v[192:195], v[124:127]
	v_mfma_f32_16x16x32_bf16 v[120:123], v[168:171], v[192:195], v[120:123]
	v_mfma_f32_16x16x32_bf16 v[108:111], v[160:163], v[200:203], v[108:111]
	v_mfma_f32_16x16x32_bf16 v[104:107], v[168:171], v[200:203], v[104:107]
	v_mfma_f32_16x16x32_bf16 v[92:95], v[160:163], v[208:211], v[92:95]
	v_mfma_f32_16x16x32_bf16 v[88:91], v[168:171], v[208:211], v[88:91]
	v_mfma_f32_16x16x32_bf16 v[76:79], v[160:163], v[216:219], v[76:79]
	v_mfma_f32_16x16x32_bf16 v[72:75], v[168:171], v[216:219], v[72:75]
	v_mfma_f32_16x16x32_bf16 v[124:127], v[164:167], v[196:199], v[124:127]
	v_mfma_f32_16x16x32_bf16 v[120:123], v[172:175], v[196:199], v[120:123]
	v_mfma_f32_16x16x32_bf16 v[108:111], v[164:167], v[204:207], v[108:111]
	v_mfma_f32_16x16x32_bf16 v[104:107], v[172:175], v[204:207], v[104:107]
	v_mfma_f32_16x16x32_bf16 v[92:95], v[164:167], v[212:215], v[92:95]
	v_mfma_f32_16x16x32_bf16 v[88:91], v[172:175], v[212:215], v[88:91]
	v_mfma_f32_16x16x32_bf16 v[76:79], v[164:167], v[220:223], v[76:79]
	v_mfma_f32_16x16x32_bf16 v[72:75], v[172:175], v[220:223], v[72:75]
	v_mfma_f32_16x16x32_bf16 v[116:119], v[176:179], v[192:195], v[116:119]
	v_mfma_f32_16x16x32_bf16 v[112:115], v[184:187], v[192:195], v[112:115]
	v_mfma_f32_16x16x32_bf16 v[100:103], v[176:179], v[200:203], v[100:103]
	v_mfma_f32_16x16x32_bf16 v[96:99], v[184:187], v[200:203], v[96:99]
	v_mfma_f32_16x16x32_bf16 v[84:87], v[176:179], v[208:211], v[84:87]
	v_mfma_f32_16x16x32_bf16 v[80:83], v[184:187], v[208:211], v[80:83]
	v_mfma_f32_16x16x32_bf16 v[68:71], v[176:179], v[216:219], v[68:71]
	v_mfma_f32_16x16x32_bf16 v[64:67], v[184:187], v[216:219], v[64:67]
	v_mfma_f32_16x16x32_bf16 v[116:119], v[180:183], v[196:199], v[116:119]
	v_mfma_f32_16x16x32_bf16 v[112:115], v[188:191], v[196:199], v[112:115]
	v_mfma_f32_16x16x32_bf16 v[100:103], v[180:183], v[204:207], v[100:103]
	v_mfma_f32_16x16x32_bf16 v[96:99], v[188:191], v[204:207], v[96:99]
	v_mfma_f32_16x16x32_bf16 v[84:87], v[180:183], v[212:215], v[84:87]
	v_mfma_f32_16x16x32_bf16 v[80:83], v[188:191], v[212:215], v[80:83]
	v_mfma_f32_16x16x32_bf16 v[68:71], v[180:183], v[220:223], v[68:71]
	v_mfma_f32_16x16x32_bf16 v[64:67], v[188:191], v[220:223], v[64:67]
	s_setprio 3
	s_barrier
	s_add_i32 s42, s57, s39
	v_lshl_add_u64 v[148:149], s[46:47], 0, v[130:131]
	s_mov_b32 m0, s42
	ds_read_b128 v[192:195], v158 offset:16384
	ds_read_b128 v[196:199], v158 offset:17408
	ds_read_b128 v[200:203], v158 offset:18432
	ds_read_b128 v[204:207], v158 offset:19456
	ds_read_b128 v[208:211], v158 offset:20480
	ds_read_b128 v[212:215], v158 offset:21504
	ds_read_b128 v[216:219], v158 offset:22528
	ds_read_b128 v[220:223], v158 offset:23552
	global_load_lds_dwordx4 v[148:149], off
	s_add_i32 m0, s42, 0x2000
	s_add_u32 s64, s46, 0x80000
	v_lshl_add_u64 v[224:225], s[46:47], 0, v[134:135]
	s_addc_u32 s65, s47, 0
	s_add_i32 s42, s58, s39
	global_load_lds_dwordx4 v[224:225], off
	v_lshl_add_u64 v[226:227], s[64:65], 0, v[130:131]
	s_mov_b32 m0, s42
	v_lshl_add_u64 v[228:229], s[52:53], 0, v[132:133]
	global_load_lds_dwordx4 v[226:227], off
	v_lshl_add_u64 v[226:227], s[64:65], 0, v[134:135]
	s_add_i32 m0, s42, 0x2000
	s_nop 0
	global_load_lds_dwordx4 v[226:227], off
	v_lshl_add_u64 v[226:227], s[52:53], 0, v[128:129]
	s_mov_b32 m0, s31
	s_nop 0
	global_load_lds_dwordx4 v[226:227], off
	s_mov_b32 m0, s44
	s_nop 0
	global_load_lds_dwordx4 v[228:229], off
	s_waitcnt vmcnt(8)
	s_waitcnt lgkmcnt(0)
	s_barrier
	s_setprio 0
	s_waitcnt lgkmcnt(0)
	v_mfma_f32_16x16x32_bf16 v[60:63], v[160:163], v[192:195], v[60:63]
	v_mfma_f32_16x16x32_bf16 v[56:59], v[168:171], v[192:195], v[56:59]
	v_mfma_f32_16x16x32_bf16 v[44:47], v[160:163], v[200:203], v[44:47]
	v_mfma_f32_16x16x32_bf16 v[40:43], v[168:171], v[200:203], v[40:43]
	v_mfma_f32_16x16x32_bf16 v[28:31], v[160:163], v[208:211], v[28:31]
	v_mfma_f32_16x16x32_bf16 v[24:27], v[168:171], v[208:211], v[24:27]
	v_mfma_f32_16x16x32_bf16 v[12:15], v[160:163], v[216:219], v[12:15]
	v_mfma_f32_16x16x32_bf16 v[8:11], v[168:171], v[216:219], v[8:11]
	v_mfma_f32_16x16x32_bf16 v[60:63], v[164:167], v[196:199], v[60:63]
	v_mfma_f32_16x16x32_bf16 v[56:59], v[172:175], v[196:199], v[56:59]
	v_mfma_f32_16x16x32_bf16 v[44:47], v[164:167], v[204:207], v[44:47]
	v_mfma_f32_16x16x32_bf16 v[40:43], v[172:175], v[204:207], v[40:43]
	v_mfma_f32_16x16x32_bf16 v[28:31], v[164:167], v[212:215], v[28:31]
	v_mfma_f32_16x16x32_bf16 v[24:27], v[172:175], v[212:215], v[24:27]
	v_mfma_f32_16x16x32_bf16 v[12:15], v[164:167], v[220:223], v[12:15]
	v_mfma_f32_16x16x32_bf16 v[8:11], v[172:175], v[220:223], v[8:11]
	v_mfma_f32_16x16x32_bf16 v[52:55], v[176:179], v[192:195], v[52:55]
	v_mfma_f32_16x16x32_bf16 v[48:51], v[184:187], v[192:195], v[48:51]
	v_mfma_f32_16x16x32_bf16 v[36:39], v[176:179], v[200:203], v[36:39]
	v_mfma_f32_16x16x32_bf16 v[32:35], v[184:187], v[200:203], v[32:35]
	v_mfma_f32_16x16x32_bf16 v[20:23], v[176:179], v[208:211], v[20:23]
	v_mfma_f32_16x16x32_bf16 v[16:19], v[184:187], v[208:211], v[16:19]
	v_mfma_f32_16x16x32_bf16 v[4:7], v[176:179], v[216:219], v[4:7]
	v_mfma_f32_16x16x32_bf16 v[0:3], v[184:187], v[216:219], v[0:3]
	v_mfma_f32_16x16x32_bf16 v[52:55], v[180:183], v[196:199], v[52:55]
	v_mfma_f32_16x16x32_bf16 v[48:51], v[188:191], v[196:199], v[48:51]
	v_mfma_f32_16x16x32_bf16 v[36:39], v[180:183], v[204:207], v[36:39]
	v_mfma_f32_16x16x32_bf16 v[32:35], v[188:191], v[204:207], v[32:35]
	v_mfma_f32_16x16x32_bf16 v[20:23], v[180:183], v[212:215], v[20:23]
	v_mfma_f32_16x16x32_bf16 v[16:19], v[188:191], v[212:215], v[16:19]
	v_mfma_f32_16x16x32_bf16 v[4:7], v[180:183], v[220:223], v[4:7]
	v_mfma_f32_16x16x32_bf16 v[0:3], v[188:191], v[220:223], v[0:3]
	s_setprio 3
	s_barrier
	s_add_i32 s42, 0, 0x18000
	v_add_u32_e32 v159, s42, v151
	s_add_i32 s43, 0, 0x1c000
	ds_read_b128 v[160:163], v159
	ds_read_b128 v[164:167], v159 offset:1024
	ds_read_b128 v[168:171], v159 offset:2048
	ds_read_b128 v[172:175], v159 offset:3072
	v_add_u32_e32 v159, s43, v151
	ds_read_b128 v[176:179], v159
	ds_read_b128 v[180:183], v159 offset:1024
	ds_read_b128 v[184:187], v159 offset:2048
	ds_read_b128 v[188:191], v159 offset:3072
	s_add_u32 s52, s52, 0x80000
	s_addc_u32 s53, s53, 0
	s_mov_b32 m0, s45
	v_lshl_add_u64 v[230:231], s[52:53], 0, v[128:129]
	ds_read_b128 v[192:195], v158 offset:32768
	ds_read_b128 v[196:199], v158 offset:33792
	ds_read_b128 v[200:203], v158 offset:34816
	ds_read_b128 v[204:207], v158 offset:35840
	ds_read_b128 v[208:211], v158 offset:36864
	ds_read_b128 v[212:215], v158 offset:37888
	ds_read_b128 v[216:219], v158 offset:38912
	ds_read_b128 v[220:223], v158 offset:39936
	global_load_lds_dwordx4 v[230:231], off
	v_lshl_add_u64 v[230:231], s[52:53], 0, v[132:133]
	s_mov_b32 m0, s48
	s_nop 0
	global_load_lds_dwordx4 v[230:231], off
	s_waitcnt vmcnt(8)
	s_waitcnt lgkmcnt(0)
	s_barrier
	s_setprio 0
	s_waitcnt lgkmcnt(0)
	v_mfma_f32_16x16x32_bf16 v[124:127], v[160:163], v[192:195], v[124:127]
	v_mfma_f32_16x16x32_bf16 v[120:123], v[168:171], v[192:195], v[120:123]
	v_mfma_f32_16x16x32_bf16 v[108:111], v[160:163], v[200:203], v[108:111]
	v_mfma_f32_16x16x32_bf16 v[104:107], v[168:171], v[200:203], v[104:107]
	v_mfma_f32_16x16x32_bf16 v[92:95], v[160:163], v[208:211], v[92:95]
	v_mfma_f32_16x16x32_bf16 v[88:91], v[168:171], v[208:211], v[88:91]
	v_mfma_f32_16x16x32_bf16 v[76:79], v[160:163], v[216:219], v[76:79]
	v_mfma_f32_16x16x32_bf16 v[72:75], v[168:171], v[216:219], v[72:75]
	v_mfma_f32_16x16x32_bf16 v[124:127], v[164:167], v[196:199], v[124:127]
	v_mfma_f32_16x16x32_bf16 v[120:123], v[172:175], v[196:199], v[120:123]
	v_mfma_f32_16x16x32_bf16 v[108:111], v[164:167], v[204:207], v[108:111]
	v_mfma_f32_16x16x32_bf16 v[104:107], v[172:175], v[204:207], v[104:107]
	v_mfma_f32_16x16x32_bf16 v[92:95], v[164:167], v[212:215], v[92:95]
	v_mfma_f32_16x16x32_bf16 v[88:91], v[172:175], v[212:215], v[88:91]
	v_mfma_f32_16x16x32_bf16 v[76:79], v[164:167], v[220:223], v[76:79]
	v_mfma_f32_16x16x32_bf16 v[72:75], v[172:175], v[220:223], v[72:75]
	v_mfma_f32_16x16x32_bf16 v[116:119], v[176:179], v[192:195], v[116:119]
	v_mfma_f32_16x16x32_bf16 v[112:115], v[184:187], v[192:195], v[112:115]
	v_mfma_f32_16x16x32_bf16 v[100:103], v[176:179], v[200:203], v[100:103]
	v_mfma_f32_16x16x32_bf16 v[96:99], v[184:187], v[200:203], v[96:99]
	v_mfma_f32_16x16x32_bf16 v[84:87], v[176:179], v[208:211], v[84:87]
	v_mfma_f32_16x16x32_bf16 v[80:83], v[184:187], v[208:211], v[80:83]
	v_mfma_f32_16x16x32_bf16 v[68:71], v[176:179], v[216:219], v[68:71]
	v_mfma_f32_16x16x32_bf16 v[64:67], v[184:187], v[216:219], v[64:67]
	v_mfma_f32_16x16x32_bf16 v[116:119], v[180:183], v[196:199], v[116:119]
	v_mfma_f32_16x16x32_bf16 v[112:115], v[188:191], v[196:199], v[112:115]
	v_mfma_f32_16x16x32_bf16 v[100:103], v[180:183], v[204:207], v[100:103]
	v_mfma_f32_16x16x32_bf16 v[96:99], v[188:191], v[204:207], v[96:99]
	v_mfma_f32_16x16x32_bf16 v[84:87], v[180:183], v[212:215], v[84:87]
	v_mfma_f32_16x16x32_bf16 v[80:83], v[188:191], v[212:215], v[80:83]
	v_mfma_f32_16x16x32_bf16 v[68:71], v[180:183], v[220:223], v[68:71]
	v_mfma_f32_16x16x32_bf16 v[64:67], v[188:191], v[220:223], v[64:67]
	s_setprio 3
	s_barrier
	s_add_i32 s42, s42, s39
	v_lshl_add_u64 v[148:149], v[148:149], 0, s[16:17]
	s_mov_b32 m0, s42
	ds_read_b128 v[192:195], v158 offset:49152
	ds_read_b128 v[196:199], v158 offset:50176
	ds_read_b128 v[200:203], v158 offset:51200
	ds_read_b128 v[204:207], v158 offset:52224
	ds_read_b128 v[208:211], v158 offset:53248
	ds_read_b128 v[212:215], v158 offset:54272
	ds_read_b128 v[216:219], v158 offset:55296
	ds_read_b128 v[220:223], v158 offset:56320
	global_load_lds_dwordx4 v[148:149], off
	s_add_i32 m0, s42, 0x2000
	s_add_u32 s46, s46, 0x80080
	v_lshl_add_u64 v[148:149], v[224:225], 0, s[16:17]
	s_addc_u32 s47, s47, 0
	s_add_i32 s42, s43, s39
	global_load_lds_dwordx4 v[148:149], off
	v_lshl_add_u64 v[148:149], s[46:47], 0, v[130:131]
	s_mov_b32 m0, s42
	s_nop 0
	global_load_lds_dwordx4 v[148:149], off
	v_lshl_add_u64 v[148:149], s[46:47], 0, v[134:135]
	s_add_i32 m0, s42, 0x2000
	s_nop 0
	global_load_lds_dwordx4 v[148:149], off
	v_lshl_add_u64 v[148:149], v[226:227], 0, s[16:17]
	s_mov_b32 m0, s54
	s_nop 0
	global_load_lds_dwordx4 v[148:149], off
	v_lshl_add_u64 v[148:149], v[228:229], 0, s[16:17]
	s_mov_b32 m0, s55
	s_nop 0
	global_load_lds_dwordx4 v[148:149], off
	s_waitcnt vmcnt(8)
	s_waitcnt lgkmcnt(0)
	s_barrier
	s_setprio 0
	s_waitcnt lgkmcnt(0)
	v_mfma_f32_16x16x32_bf16 v[60:63], v[160:163], v[192:195], v[60:63]
	v_mfma_f32_16x16x32_bf16 v[56:59], v[168:171], v[192:195], v[56:59]
	v_mfma_f32_16x16x32_bf16 v[44:47], v[160:163], v[200:203], v[44:47]
	v_mfma_f32_16x16x32_bf16 v[40:43], v[168:171], v[200:203], v[40:43]
	v_mfma_f32_16x16x32_bf16 v[28:31], v[160:163], v[208:211], v[28:31]
	v_mfma_f32_16x16x32_bf16 v[24:27], v[168:171], v[208:211], v[24:27]
	v_mfma_f32_16x16x32_bf16 v[12:15], v[160:163], v[216:219], v[12:15]
	v_mfma_f32_16x16x32_bf16 v[8:11], v[168:171], v[216:219], v[8:11]
	v_mfma_f32_16x16x32_bf16 v[60:63], v[164:167], v[196:199], v[60:63]
	v_mfma_f32_16x16x32_bf16 v[56:59], v[172:175], v[196:199], v[56:59]
	v_mfma_f32_16x16x32_bf16 v[44:47], v[164:167], v[204:207], v[44:47]
	v_mfma_f32_16x16x32_bf16 v[40:43], v[172:175], v[204:207], v[40:43]
	v_mfma_f32_16x16x32_bf16 v[28:31], v[164:167], v[212:215], v[28:31]
	v_mfma_f32_16x16x32_bf16 v[24:27], v[172:175], v[212:215], v[24:27]
	v_mfma_f32_16x16x32_bf16 v[12:15], v[164:167], v[220:223], v[12:15]
	v_mfma_f32_16x16x32_bf16 v[8:11], v[172:175], v[220:223], v[8:11]
	v_mfma_f32_16x16x32_bf16 v[52:55], v[176:179], v[192:195], v[52:55]
	v_mfma_f32_16x16x32_bf16 v[48:51], v[184:187], v[192:195], v[48:51]
	v_mfma_f32_16x16x32_bf16 v[36:39], v[176:179], v[200:203], v[36:39]
	v_mfma_f32_16x16x32_bf16 v[32:35], v[184:187], v[200:203], v[32:35]
	v_mfma_f32_16x16x32_bf16 v[20:23], v[176:179], v[208:211], v[20:23]
	v_mfma_f32_16x16x32_bf16 v[16:19], v[184:187], v[208:211], v[16:19]
	v_mfma_f32_16x16x32_bf16 v[4:7], v[176:179], v[216:219], v[4:7]
	v_mfma_f32_16x16x32_bf16 v[0:3], v[184:187], v[216:219], v[0:3]
	v_mfma_f32_16x16x32_bf16 v[52:55], v[180:183], v[196:199], v[52:55]
	v_mfma_f32_16x16x32_bf16 v[48:51], v[188:191], v[196:199], v[48:51]
	v_mfma_f32_16x16x32_bf16 v[36:39], v[180:183], v[204:207], v[36:39]
	v_mfma_f32_16x16x32_bf16 v[32:35], v[188:191], v[204:207], v[32:35]
	v_mfma_f32_16x16x32_bf16 v[20:23], v[180:183], v[212:215], v[20:23]
	v_mfma_f32_16x16x32_bf16 v[16:19], v[188:191], v[212:215], v[16:19]
	v_mfma_f32_16x16x32_bf16 v[4:7], v[180:183], v[220:223], v[4:7]
	v_mfma_f32_16x16x32_bf16 v[0:3], v[188:191], v[220:223], v[0:3]
	s_setprio 3
	s_barrier
	s_add_i32 s63, s63, 2
	v_lshl_add_u64 v[144:145], v[144:145], 0, s[20:21]
	v_lshl_add_u64 v[146:147], v[146:147], 0, s[20:21]
	s_cbranch_vccz .LBB0_574
	s_and_b64 vcc, exec, s[18:19]
	s_cbranch_vccz .LBB0_577
	s_barrier

.LBB0_665:
	s_add_i32 s26, s34, s61
	s_cmpk_lt_u32 s26, 0x58
	s_cselect_b32 s27, 0, 0xffffffa8
	s_add_i32 s28, s26, s27
	s_cmpk_lt_i32 s28, 0x56
	s_cselect_b32 s29, 0, 0xffffffa8
	ds_read_b128 v[140:143], v147
	ds_read_b128 v[150:153], v147 offset:1024
	ds_read_b128 v[154:157], v147 offset:2048
	ds_read_b128 v[158:161], v147 offset:3072
	ds_read_b128 v[162:165], v148
	ds_read_b128 v[166:169], v148 offset:1024
	ds_read_b128 v[170:173], v148 offset:2048
	ds_read_b128 v[174:177], v148 offset:3072
	s_add_i32 s27, s27, s29
	s_add_i32 s26, s26, s27
	s_add_i32 s26, s26, 2
	s_add_i32 s62, s28, 1
	s_ashr_i32 s27, s26, 31
	s_ashr_i32 s63, s62, 31
	s_lshl_b64 s[26:27], s[26:27], 7
	s_add_u32 s28, s24, s26
	s_addc_u32 s29, s25, s27
	s_add_u32 s26, s22, s26
	s_addc_u32 s27, s23, s27
	s_cmpk_eq_i32 s61, 0x56
	s_cselect_b32 s29, s58, s29
	s_cselect_b32 s28, s57, s28
	s_cselect_b32 s27, s60, s27
	s_cselect_b32 s26, s59, s26
	s_lshl_b64 s[62:63], s[62:63], 7
	s_add_u32 s62, s55, s62
	s_addc_u32 s63, s56, s63
	v_lshl_add_u64 v[210:211], s[62:63], 0, v[128:129]
	s_add_i32 m0, s39, 0xc000
	ds_read_b128 v[178:181], v149
	ds_read_b128 v[182:185], v149 offset:1024
	ds_read_b128 v[186:189], v149 offset:2048
	ds_read_b128 v[190:193], v149 offset:3072
	ds_read_b128 v[194:197], v149 offset:4096
	ds_read_b128 v[198:201], v149 offset:5120
	ds_read_b128 v[202:205], v149 offset:6144
	ds_read_b128 v[206:209], v149 offset:7168
	global_load_lds_dwordx4 v[210:211], off
	v_lshl_add_u64 v[210:211], s[62:63], 0, v[132:133]
	s_add_i32 m0, s39, 0xe000
	s_nop 0
	global_load_lds_dwordx4 v[210:211], off
	s_waitcnt vmcnt(8)
	s_waitcnt lgkmcnt(0)
	s_barrier
	s_setprio 0
	s_waitcnt lgkmcnt(0)
	v_mfma_f32_16x16x32_bf16 v[124:127], v[140:143], v[178:181], v[124:127]
	v_mfma_f32_16x16x32_bf16 v[120:123], v[154:157], v[178:181], v[120:123]
	v_mfma_f32_16x16x32_bf16 v[116:119], v[140:143], v[186:189], v[116:119]
	v_mfma_f32_16x16x32_bf16 v[108:111], v[154:157], v[186:189], v[108:111]
	v_mfma_f32_16x16x32_bf16 v[100:103], v[140:143], v[194:197], v[100:103]
	v_mfma_f32_16x16x32_bf16 v[92:95], v[154:157], v[194:197], v[92:95]
	v_mfma_f32_16x16x32_bf16 v[84:87], v[140:143], v[202:205], v[84:87]
	v_mfma_f32_16x16x32_bf16 v[76:79], v[154:157], v[202:205], v[76:79]
	v_mfma_f32_16x16x32_bf16 v[124:127], v[150:153], v[182:185], v[124:127]
	v_mfma_f32_16x16x32_bf16 v[120:123], v[158:161], v[182:185], v[120:123]
	v_mfma_f32_16x16x32_bf16 v[116:119], v[150:153], v[190:193], v[116:119]
	v_mfma_f32_16x16x32_bf16 v[108:111], v[158:161], v[190:193], v[108:111]
	v_mfma_f32_16x16x32_bf16 v[100:103], v[150:153], v[198:201], v[100:103]
	v_mfma_f32_16x16x32_bf16 v[92:95], v[158:161], v[198:201], v[92:95]
	v_mfma_f32_16x16x32_bf16 v[84:87], v[150:153], v[206:209], v[84:87]
	v_mfma_f32_16x16x32_bf16 v[76:79], v[158:161], v[206:209], v[76:79]
	v_mfma_f32_16x16x32_bf16 v[112:115], v[162:165], v[178:181], v[112:115]
	v_mfma_f32_16x16x32_bf16 v[104:107], v[170:173], v[178:181], v[104:107]
	v_mfma_f32_16x16x32_bf16 v[96:99], v[162:165], v[186:189], v[96:99]
	v_mfma_f32_16x16x32_bf16 v[88:91], v[170:173], v[186:189], v[88:91]
	v_mfma_f32_16x16x32_bf16 v[80:83], v[162:165], v[194:197], v[80:83]
	v_mfma_f32_16x16x32_bf16 v[72:75], v[170:173], v[194:197], v[72:75]
	v_mfma_f32_16x16x32_bf16 v[68:71], v[162:165], v[202:205], v[68:71]
	v_mfma_f32_16x16x32_bf16 v[64:67], v[170:173], v[202:205], v[64:67]
	v_mfma_f32_16x16x32_bf16 v[112:115], v[166:169], v[182:185], v[112:115]
	v_mfma_f32_16x16x32_bf16 v[104:107], v[174:177], v[182:185], v[104:107]
	v_mfma_f32_16x16x32_bf16 v[96:99], v[166:169], v[190:193], v[96:99]
	v_mfma_f32_16x16x32_bf16 v[88:91], v[174:177], v[190:193], v[88:91]
	v_mfma_f32_16x16x32_bf16 v[80:83], v[166:169], v[198:201], v[80:83]
	v_mfma_f32_16x16x32_bf16 v[72:75], v[174:177], v[198:201], v[72:75]
	v_mfma_f32_16x16x32_bf16 v[68:71], v[166:169], v[206:209], v[68:71]
	v_mfma_f32_16x16x32_bf16 v[64:67], v[174:177], v[206:209], v[64:67]
	s_setprio 3
	s_barrier
	s_add_i32 s42, s49, s35
	v_lshl_add_u64 v[210:211], s[26:27], 0, v[130:131]
	s_mov_b32 m0, s42
	ds_read_b128 v[178:181], v149 offset:16384
	ds_read_b128 v[182:185], v149 offset:17408
	ds_read_b128 v[186:189], v149 offset:18432
	ds_read_b128 v[190:193], v149 offset:19456
	ds_read_b128 v[194:197], v149 offset:20480
	ds_read_b128 v[198:201], v149 offset:21504
	ds_read_b128 v[202:205], v149 offset:22528
	ds_read_b128 v[206:209], v149 offset:23552
	global_load_lds_dwordx4 v[210:211], off
	s_add_i32 m0, s42, 0x2000
	s_add_u32 s62, s26, 0x160000
	v_lshl_add_u64 v[212:213], s[26:27], 0, v[134:135]
	s_addc_u32 s63, s27, 0
	s_add_i32 s42, s50, s35
	global_load_lds_dwordx4 v[212:213], off
	v_lshl_add_u64 v[214:215], s[62:63], 0, v[130:131]
	s_mov_b32 m0, s42
	v_lshl_add_u64 v[216:217], s[28:29], 0, v[132:133]
	global_load_lds_dwordx4 v[214:215], off
	v_lshl_add_u64 v[214:215], s[62:63], 0, v[134:135]
	s_add_i32 m0, s42, 0x2000
	s_nop 0
	global_load_lds_dwordx4 v[214:215], off
	v_lshl_add_u64 v[214:215], s[28:29], 0, v[128:129]
	s_mov_b32 m0, s39
	s_nop 0
	global_load_lds_dwordx4 v[214:215], off
	s_mov_b32 m0, s40
	s_nop 0
	global_load_lds_dwordx4 v[216:217], off
	s_waitcnt vmcnt(8)
	s_waitcnt lgkmcnt(0)
	s_barrier
	s_setprio 0
	s_waitcnt lgkmcnt(0)
	v_mfma_f32_16x16x32_bf16 v[60:63], v[140:143], v[178:181], v[60:63]
	v_mfma_f32_16x16x32_bf16 v[56:59], v[154:157], v[178:181], v[56:59]
	v_mfma_f32_16x16x32_bf16 v[52:55], v[140:143], v[186:189], v[52:55]
	v_mfma_f32_16x16x32_bf16 v[44:47], v[154:157], v[186:189], v[44:47]
	v_mfma_f32_16x16x32_bf16 v[36:39], v[140:143], v[194:197], v[36:39]
	v_mfma_f32_16x16x32_bf16 v[28:31], v[154:157], v[194:197], v[28:31]
	v_mfma_f32_16x16x32_bf16 v[20:23], v[140:143], v[202:205], v[20:23]
	v_mfma_f32_16x16x32_bf16 v[12:15], v[154:157], v[202:205], v[12:15]
	v_mfma_f32_16x16x32_bf16 v[60:63], v[150:153], v[182:185], v[60:63]
	v_mfma_f32_16x16x32_bf16 v[56:59], v[158:161], v[182:185], v[56:59]
	v_mfma_f32_16x16x32_bf16 v[52:55], v[150:153], v[190:193], v[52:55]
	v_mfma_f32_16x16x32_bf16 v[44:47], v[158:161], v[190:193], v[44:47]
	v_mfma_f32_16x16x32_bf16 v[36:39], v[150:153], v[198:201], v[36:39]
	v_mfma_f32_16x16x32_bf16 v[28:31], v[158:161], v[198:201], v[28:31]
	v_mfma_f32_16x16x32_bf16 v[20:23], v[150:153], v[206:209], v[20:23]
	v_mfma_f32_16x16x32_bf16 v[12:15], v[158:161], v[206:209], v[12:15]
	v_mfma_f32_16x16x32_bf16 v[48:51], v[162:165], v[178:181], v[48:51]
	v_mfma_f32_16x16x32_bf16 v[40:43], v[170:173], v[178:181], v[40:43]
	v_mfma_f32_16x16x32_bf16 v[32:35], v[162:165], v[186:189], v[32:35]
	v_mfma_f32_16x16x32_bf16 v[24:27], v[170:173], v[186:189], v[24:27]
	v_mfma_f32_16x16x32_bf16 v[16:19], v[162:165], v[194:197], v[16:19]
	v_mfma_f32_16x16x32_bf16 v[8:11], v[170:173], v[194:197], v[8:11]
	v_mfma_f32_16x16x32_bf16 v[4:7], v[162:165], v[202:205], v[4:7]
	v_mfma_f32_16x16x32_bf16 v[0:3], v[170:173], v[202:205], v[0:3]
	v_mfma_f32_16x16x32_bf16 v[48:51], v[166:169], v[182:185], v[48:51]
	v_mfma_f32_16x16x32_bf16 v[40:43], v[174:177], v[182:185], v[40:43]
	v_mfma_f32_16x16x32_bf16 v[32:35], v[166:169], v[190:193], v[32:35]
	v_mfma_f32_16x16x32_bf16 v[24:27], v[174:177], v[190:193], v[24:27]
	v_mfma_f32_16x16x32_bf16 v[16:19], v[166:169], v[198:201], v[16:19]
	v_mfma_f32_16x16x32_bf16 v[8:11], v[174:177], v[198:201], v[8:11]
	v_mfma_f32_16x16x32_bf16 v[4:7], v[166:169], v[206:209], v[4:7]
	v_mfma_f32_16x16x32_bf16 v[0:3], v[174:177], v[206:209], v[0:3]
	s_setprio 3
	s_barrier
	s_add_i32 s42, 0, 0x18000
	s_add_i32 s43, 0, 0x1c000
	v_add_u32_e32 v158, s42, v145
	v_add_u32_e32 v174, s43, v145
	ds_read_b128 v[140:143], v158
	ds_read_b128 v[150:153], v158 offset:1024
	ds_read_b128 v[154:157], v158 offset:2048
	ds_read_b128 v[158:161], v158 offset:3072
	ds_read_b128 v[162:165], v174
	ds_read_b128 v[166:169], v174 offset:1024
	ds_read_b128 v[170:173], v174 offset:2048
	ds_read_b128 v[174:177], v174 offset:3072
	s_add_u32 s28, s28, 0x160000
	s_addc_u32 s29, s29, 0
	s_mov_b32 m0, s41
	v_lshl_add_u64 v[218:219], s[28:29], 0, v[128:129]
	ds_read_b128 v[178:181], v149 offset:32768
	ds_read_b128 v[182:185], v149 offset:33792
	ds_read_b128 v[186:189], v149 offset:34816
	ds_read_b128 v[190:193], v149 offset:35840
	ds_read_b128 v[194:197], v149 offset:36864
	ds_read_b128 v[198:201], v149 offset:37888
	ds_read_b128 v[202:205], v149 offset:38912
	ds_read_b128 v[206:209], v149 offset:39936
	global_load_lds_dwordx4 v[218:219], off
	v_lshl_add_u64 v[218:219], s[28:29], 0, v[132:133]
	s_mov_b32 m0, s44
	s_nop 0
	global_load_lds_dwordx4 v[218:219], off
	s_waitcnt vmcnt(8)
	s_waitcnt lgkmcnt(0)
	s_barrier
	s_setprio 0
	s_waitcnt lgkmcnt(0)
	v_mfma_f32_16x16x32_bf16 v[124:127], v[140:143], v[178:181], v[124:127]
	v_mfma_f32_16x16x32_bf16 v[120:123], v[154:157], v[178:181], v[120:123]
	v_mfma_f32_16x16x32_bf16 v[116:119], v[140:143], v[186:189], v[116:119]
	v_mfma_f32_16x16x32_bf16 v[108:111], v[154:157], v[186:189], v[108:111]
	v_mfma_f32_16x16x32_bf16 v[100:103], v[140:143], v[194:197], v[100:103]
	v_mfma_f32_16x16x32_bf16 v[92:95], v[154:157], v[194:197], v[92:95]
	v_mfma_f32_16x16x32_bf16 v[84:87], v[140:143], v[202:205], v[84:87]
	v_mfma_f32_16x16x32_bf16 v[76:79], v[154:157], v[202:205], v[76:79]
	v_mfma_f32_16x16x32_bf16 v[124:127], v[150:153], v[182:185], v[124:127]
	v_mfma_f32_16x16x32_bf16 v[120:123], v[158:161], v[182:185], v[120:123]
	v_mfma_f32_16x16x32_bf16 v[116:119], v[150:153], v[190:193], v[116:119]
	v_mfma_f32_16x16x32_bf16 v[108:111], v[158:161], v[190:193], v[108:111]
	v_mfma_f32_16x16x32_bf16 v[100:103], v[150:153], v[198:201], v[100:103]
	v_mfma_f32_16x16x32_bf16 v[92:95], v[158:161], v[198:201], v[92:95]
	v_mfma_f32_16x16x32_bf16 v[84:87], v[150:153], v[206:209], v[84:87]
	v_mfma_f32_16x16x32_bf16 v[76:79], v[158:161], v[206:209], v[76:79]
	v_mfma_f32_16x16x32_bf16 v[112:115], v[162:165], v[178:181], v[112:115]
	v_mfma_f32_16x16x32_bf16 v[104:107], v[170:173], v[178:181], v[104:107]
	v_mfma_f32_16x16x32_bf16 v[96:99], v[162:165], v[186:189], v[96:99]
	v_mfma_f32_16x16x32_bf16 v[88:91], v[170:173], v[186:189], v[88:91]
	v_mfma_f32_16x16x32_bf16 v[80:83], v[162:165], v[194:197], v[80:83]
	v_mfma_f32_16x16x32_bf16 v[72:75], v[170:173], v[194:197], v[72:75]
	v_mfma_f32_16x16x32_bf16 v[68:71], v[162:165], v[202:205], v[68:71]
	v_mfma_f32_16x16x32_bf16 v[64:67], v[170:173], v[202:205], v[64:67]
	v_mfma_f32_16x16x32_bf16 v[112:115], v[166:169], v[182:185], v[112:115]
	v_mfma_f32_16x16x32_bf16 v[104:107], v[174:177], v[182:185], v[104:107]
	v_mfma_f32_16x16x32_bf16 v[96:99], v[166:169], v[190:193], v[96:99]
	v_mfma_f32_16x16x32_bf16 v[88:91], v[174:177], v[190:193], v[88:91]
	v_mfma_f32_16x16x32_bf16 v[80:83], v[166:169], v[198:201], v[80:83]
	v_mfma_f32_16x16x32_bf16 v[72:75], v[174:177], v[198:201], v[72:75]
	v_mfma_f32_16x16x32_bf16 v[68:71], v[166:169], v[206:209], v[68:71]
	v_mfma_f32_16x16x32_bf16 v[64:67], v[174:177], v[206:209], v[64:67]
	s_setprio 3
	s_barrier
	s_add_i32 s28, s42, s35
	v_lshl_add_u64 v[210:211], v[210:211], 0, s[16:17]
	s_mov_b32 m0, s28
	ds_read_b128 v[178:181], v149 offset:49152
	ds_read_b128 v[182:185], v149 offset:50176
	ds_read_b128 v[186:189], v149 offset:51200
	ds_read_b128 v[190:193], v149 offset:52224
	ds_read_b128 v[194:197], v149 offset:53248
	ds_read_b128 v[198:201], v149 offset:54272
	ds_read_b128 v[202:205], v149 offset:55296
	ds_read_b128 v[206:209], v149 offset:56320
	global_load_lds_dwordx4 v[210:211], off
	s_add_i32 m0, s28, 0x2000
	s_add_u32 s26, s26, 0x160080
	v_lshl_add_u64 v[210:211], v[212:213], 0, s[16:17]
	s_addc_u32 s27, s27, 0
	s_add_i32 s28, s43, s35
	global_load_lds_dwordx4 v[210:211], off
	v_lshl_add_u64 v[210:211], s[26:27], 0, v[130:131]
	s_mov_b32 m0, s28
	s_nop 0
	global_load_lds_dwordx4 v[210:211], off
	v_lshl_add_u64 v[210:211], s[26:27], 0, v[134:135]
	s_add_i32 m0, s28, 0x2000
	s_nop 0
	global_load_lds_dwordx4 v[210:211], off
	v_lshl_add_u64 v[210:211], v[214:215], 0, s[16:17]
	s_mov_b32 m0, s46
	s_nop 0
	global_load_lds_dwordx4 v[210:211], off
	v_lshl_add_u64 v[210:211], v[216:217], 0, s[16:17]
	s_mov_b32 m0, s47
	s_nop 0
	global_load_lds_dwordx4 v[210:211], off
	s_waitcnt vmcnt(8)
	s_waitcnt lgkmcnt(0)
	s_barrier
	s_setprio 0
	s_waitcnt lgkmcnt(0)
	v_mfma_f32_16x16x32_bf16 v[60:63], v[140:143], v[178:181], v[60:63]
	v_mfma_f32_16x16x32_bf16 v[56:59], v[154:157], v[178:181], v[56:59]
	v_mfma_f32_16x16x32_bf16 v[52:55], v[140:143], v[186:189], v[52:55]
	v_mfma_f32_16x16x32_bf16 v[44:47], v[154:157], v[186:189], v[44:47]
	v_mfma_f32_16x16x32_bf16 v[36:39], v[140:143], v[194:197], v[36:39]
	v_mfma_f32_16x16x32_bf16 v[28:31], v[154:157], v[194:197], v[28:31]
	v_mfma_f32_16x16x32_bf16 v[20:23], v[140:143], v[202:205], v[20:23]
	v_mfma_f32_16x16x32_bf16 v[12:15], v[154:157], v[202:205], v[12:15]
	v_mfma_f32_16x16x32_bf16 v[60:63], v[150:153], v[182:185], v[60:63]
	v_mfma_f32_16x16x32_bf16 v[56:59], v[158:161], v[182:185], v[56:59]
	v_mfma_f32_16x16x32_bf16 v[52:55], v[150:153], v[190:193], v[52:55]
	v_mfma_f32_16x16x32_bf16 v[44:47], v[158:161], v[190:193], v[44:47]
	v_mfma_f32_16x16x32_bf16 v[36:39], v[150:153], v[198:201], v[36:39]
	v_mfma_f32_16x16x32_bf16 v[28:31], v[158:161], v[198:201], v[28:31]
	v_mfma_f32_16x16x32_bf16 v[20:23], v[150:153], v[206:209], v[20:23]
	v_mfma_f32_16x16x32_bf16 v[12:15], v[158:161], v[206:209], v[12:15]
	v_mfma_f32_16x16x32_bf16 v[48:51], v[162:165], v[178:181], v[48:51]
	v_mfma_f32_16x16x32_bf16 v[40:43], v[170:173], v[178:181], v[40:43]
	v_mfma_f32_16x16x32_bf16 v[32:35], v[162:165], v[186:189], v[32:35]
	v_mfma_f32_16x16x32_bf16 v[24:27], v[170:173], v[186:189], v[24:27]
	v_mfma_f32_16x16x32_bf16 v[16:19], v[162:165], v[194:197], v[16:19]
	v_mfma_f32_16x16x32_bf16 v[8:11], v[170:173], v[194:197], v[8:11]
	v_mfma_f32_16x16x32_bf16 v[4:7], v[162:165], v[202:205], v[4:7]
	v_mfma_f32_16x16x32_bf16 v[0:3], v[170:173], v[202:205], v[0:3]
	v_mfma_f32_16x16x32_bf16 v[48:51], v[166:169], v[182:185], v[48:51]
	v_mfma_f32_16x16x32_bf16 v[40:43], v[174:177], v[182:185], v[40:43]
	v_mfma_f32_16x16x32_bf16 v[32:35], v[166:169], v[190:193], v[32:35]
	v_mfma_f32_16x16x32_bf16 v[24:27], v[174:177], v[190:193], v[24:27]
	v_mfma_f32_16x16x32_bf16 v[16:19], v[166:169], v[198:201], v[16:19]
	v_mfma_f32_16x16x32_bf16 v[8:11], v[174:177], v[198:201], v[8:11]
	v_mfma_f32_16x16x32_bf16 v[4:7], v[166:169], v[206:209], v[4:7]
	v_mfma_f32_16x16x32_bf16 v[0:3], v[174:177], v[206:209], v[0:3]
	s_setprio 3
	s_barrier
	s_add_i32 s26, s61, 2
	s_cmpk_gt_u32 s61, 0x55
	s_mov_b32 s61, s26
	s_cbranch_scc0 .LBB0_665
	s_and_b64 vcc, exec, s[18:19]
	s_cbranch_vccz .LBB0_668
	s_barrier

.LBB0_812:
	s_cmp_gt_u32 s85, 29
	s_cselect_b64 s[4:5], -1, 0
	ds_read_b128 v[132:135], v169
	ds_read_b128 v[154:157], v169 offset:1024
	ds_read_b128 v[158:161], v169 offset:2048
	ds_read_b128 v[162:165], v169 offset:3072
	ds_read_b128 v[172:175], v170
	ds_read_b128 v[176:179], v170 offset:1024
	ds_read_b128 v[180:183], v170 offset:2048
	ds_read_b128 v[184:187], v170 offset:3072
	s_and_b64 vcc, s[4:5], exec
	s_cselect_b32 s4, 0xffffffe2, 2
	s_add_i32 s4, s4, s85
	s_ashr_i32 s5, s4, 31
	s_lshl_b64 s[4:5], s[4:5], 7
	s_add_u32 s42, s92, s4
	s_addc_u32 s43, s93, s5
	s_add_u32 s4, s6, s4
	s_addc_u32 s5, s7, s5
	s_cmp_eq_u32 s85, 30
	s_cselect_b32 s47, s9, s43
	s_cselect_b32 s46, s40, s42
	s_cselect_b32 s5, s41, s5
	s_cselect_b32 s4, s83, s4
	s_add_i32 m0, s72, 0xc000
	ds_read_b128 v[188:191], v171
	ds_read_b128 v[192:195], v171 offset:1024
	ds_read_b128 v[196:199], v171 offset:2048
	ds_read_b128 v[200:203], v171 offset:3072
	ds_read_b128 v[204:207], v171 offset:4096
	ds_read_b128 v[208:211], v171 offset:5120
	ds_read_b128 v[212:215], v171 offset:6144
	ds_read_b128 v[216:219], v171 offset:7168
	global_load_lds_dwordx4 v[128:129], off
	s_add_i32 m0, s72, 0xe000
	s_nop 0
	global_load_lds_dwordx4 v[130:131], off
	s_waitcnt vmcnt(8)
	s_waitcnt lgkmcnt(0)
	s_barrier
	s_setprio 0
	s_waitcnt lgkmcnt(0)
	v_mfma_f32_16x16x32_bf16 v[124:127], v[132:135], v[188:191], v[124:127]
	v_mfma_f32_16x16x32_bf16 v[120:123], v[158:161], v[188:191], v[120:123]
	v_mfma_f32_16x16x32_bf16 v[108:111], v[132:135], v[196:199], v[108:111]
	v_mfma_f32_16x16x32_bf16 v[104:107], v[158:161], v[196:199], v[104:107]
	v_mfma_f32_16x16x32_bf16 v[92:95], v[132:135], v[204:207], v[92:95]
	v_mfma_f32_16x16x32_bf16 v[88:91], v[158:161], v[204:207], v[88:91]
	v_mfma_f32_16x16x32_bf16 v[76:79], v[132:135], v[212:215], v[76:79]
	v_mfma_f32_16x16x32_bf16 v[72:75], v[158:161], v[212:215], v[72:75]
	v_mfma_f32_16x16x32_bf16 v[124:127], v[154:157], v[192:195], v[124:127]
	v_mfma_f32_16x16x32_bf16 v[120:123], v[162:165], v[192:195], v[120:123]
	v_mfma_f32_16x16x32_bf16 v[108:111], v[154:157], v[200:203], v[108:111]
	v_mfma_f32_16x16x32_bf16 v[104:107], v[162:165], v[200:203], v[104:107]
	v_mfma_f32_16x16x32_bf16 v[92:95], v[154:157], v[208:211], v[92:95]
	v_mfma_f32_16x16x32_bf16 v[88:91], v[162:165], v[208:211], v[88:91]
	v_mfma_f32_16x16x32_bf16 v[76:79], v[154:157], v[216:219], v[76:79]
	v_mfma_f32_16x16x32_bf16 v[72:75], v[162:165], v[216:219], v[72:75]
	v_mfma_f32_16x16x32_bf16 v[116:119], v[172:175], v[188:191], v[116:119]
	v_mfma_f32_16x16x32_bf16 v[112:115], v[180:183], v[188:191], v[112:115]
	v_mfma_f32_16x16x32_bf16 v[100:103], v[172:175], v[196:199], v[100:103]
	v_mfma_f32_16x16x32_bf16 v[96:99], v[180:183], v[196:199], v[96:99]
	v_mfma_f32_16x16x32_bf16 v[84:87], v[172:175], v[204:207], v[84:87]
	v_mfma_f32_16x16x32_bf16 v[80:83], v[180:183], v[204:207], v[80:83]
	v_mfma_f32_16x16x32_bf16 v[68:71], v[172:175], v[212:215], v[68:71]
	v_mfma_f32_16x16x32_bf16 v[64:67], v[180:183], v[212:215], v[64:67]
	v_mfma_f32_16x16x32_bf16 v[116:119], v[176:179], v[192:195], v[116:119]
	v_mfma_f32_16x16x32_bf16 v[112:115], v[184:187], v[192:195], v[112:115]
	v_mfma_f32_16x16x32_bf16 v[100:103], v[176:179], v[200:203], v[100:103]
	v_mfma_f32_16x16x32_bf16 v[96:99], v[184:187], v[200:203], v[96:99]
	v_mfma_f32_16x16x32_bf16 v[84:87], v[176:179], v[208:211], v[84:87]
	v_mfma_f32_16x16x32_bf16 v[80:83], v[184:187], v[208:211], v[80:83]
	v_mfma_f32_16x16x32_bf16 v[68:71], v[176:179], v[216:219], v[68:71]
	v_mfma_f32_16x16x32_bf16 v[64:67], v[184:187], v[216:219], v[64:67]
	s_setprio 3
	s_barrier
	s_add_i32 s42, s37, s71
	v_lshl_add_u64 v[220:221], s[4:5], 0, v[138:139]
	s_mov_b32 m0, s42
	ds_read_b128 v[188:191], v171 offset:16384
	ds_read_b128 v[192:195], v171 offset:17408
	ds_read_b128 v[196:199], v171 offset:18432
	ds_read_b128 v[200:203], v171 offset:19456
	ds_read_b128 v[204:207], v171 offset:20480
	ds_read_b128 v[208:211], v171 offset:21504
	ds_read_b128 v[212:215], v171 offset:22528
	ds_read_b128 v[216:219], v171 offset:23552
	global_load_lds_dwordx4 v[220:221], off
	s_add_i32 m0, s42, 0x2000
	s_add_u32 s94, s4, 0x80000
	v_lshl_add_u64 v[222:223], s[4:5], 0, v[142:143]
	s_addc_u32 s95, s5, 0
	s_add_i32 s42, s56, s71
	global_load_lds_dwordx4 v[222:223], off
	v_lshl_add_u64 v[224:225], s[94:95], 0, v[138:139]
	s_mov_b32 m0, s42
	v_lshl_add_u64 v[226:227], s[46:47], 0, v[140:141]
	global_load_lds_dwordx4 v[224:225], off
	v_lshl_add_u64 v[224:225], s[94:95], 0, v[142:143]
	s_add_i32 m0, s42, 0x2000
	s_nop 0
	global_load_lds_dwordx4 v[224:225], off
	v_lshl_add_u64 v[224:225], s[46:47], 0, v[136:137]
	s_mov_b32 m0, s72
	s_nop 0
	global_load_lds_dwordx4 v[224:225], off
	s_mov_b32 m0, s74
	s_nop 0
	global_load_lds_dwordx4 v[226:227], off
	s_waitcnt vmcnt(8)
	s_waitcnt lgkmcnt(0)
	s_barrier
	s_setprio 0
	s_waitcnt lgkmcnt(0)
	v_mfma_f32_16x16x32_bf16 v[60:63], v[132:135], v[188:191], v[60:63]
	v_mfma_f32_16x16x32_bf16 v[56:59], v[158:161], v[188:191], v[56:59]
	v_mfma_f32_16x16x32_bf16 v[44:47], v[132:135], v[196:199], v[44:47]
	v_mfma_f32_16x16x32_bf16 v[40:43], v[158:161], v[196:199], v[40:43]
	v_mfma_f32_16x16x32_bf16 v[28:31], v[132:135], v[204:207], v[28:31]
	v_mfma_f32_16x16x32_bf16 v[24:27], v[158:161], v[204:207], v[24:27]
	v_mfma_f32_16x16x32_bf16 v[12:15], v[132:135], v[212:215], v[12:15]
	v_mfma_f32_16x16x32_bf16 v[8:11], v[158:161], v[212:215], v[8:11]
	v_mfma_f32_16x16x32_bf16 v[60:63], v[154:157], v[192:195], v[60:63]
	v_mfma_f32_16x16x32_bf16 v[56:59], v[162:165], v[192:195], v[56:59]
	v_mfma_f32_16x16x32_bf16 v[44:47], v[154:157], v[200:203], v[44:47]
	v_mfma_f32_16x16x32_bf16 v[40:43], v[162:165], v[200:203], v[40:43]
	v_mfma_f32_16x16x32_bf16 v[28:31], v[154:157], v[208:211], v[28:31]
	v_mfma_f32_16x16x32_bf16 v[24:27], v[162:165], v[208:211], v[24:27]
	v_mfma_f32_16x16x32_bf16 v[12:15], v[154:157], v[216:219], v[12:15]
	v_mfma_f32_16x16x32_bf16 v[8:11], v[162:165], v[216:219], v[8:11]
	v_mfma_f32_16x16x32_bf16 v[52:55], v[172:175], v[188:191], v[52:55]
	v_mfma_f32_16x16x32_bf16 v[48:51], v[180:183], v[188:191], v[48:51]
	v_mfma_f32_16x16x32_bf16 v[36:39], v[172:175], v[196:199], v[36:39]
	v_mfma_f32_16x16x32_bf16 v[32:35], v[180:183], v[196:199], v[32:35]
	v_mfma_f32_16x16x32_bf16 v[20:23], v[172:175], v[204:207], v[20:23]
	v_mfma_f32_16x16x32_bf16 v[16:19], v[180:183], v[204:207], v[16:19]
	v_mfma_f32_16x16x32_bf16 v[4:7], v[172:175], v[212:215], v[4:7]
	v_mfma_f32_16x16x32_bf16 v[0:3], v[180:183], v[212:215], v[0:3]
	v_mfma_f32_16x16x32_bf16 v[52:55], v[176:179], v[192:195], v[52:55]
	v_mfma_f32_16x16x32_bf16 v[48:51], v[184:187], v[192:195], v[48:51]
	v_mfma_f32_16x16x32_bf16 v[36:39], v[176:179], v[200:203], v[36:39]
	v_mfma_f32_16x16x32_bf16 v[32:35], v[184:187], v[200:203], v[32:35]
	v_mfma_f32_16x16x32_bf16 v[20:23], v[176:179], v[208:211], v[20:23]
	v_mfma_f32_16x16x32_bf16 v[16:19], v[184:187], v[208:211], v[16:19]
	v_mfma_f32_16x16x32_bf16 v[4:7], v[176:179], v[216:219], v[4:7]
	v_mfma_f32_16x16x32_bf16 v[0:3], v[184:187], v[216:219], v[0:3]
	s_setprio 3
	s_barrier
	s_add_i32 s42, 0, 0x18000
	v_add_u32_e32 v144, s42, v167
	s_add_i32 s43, 0, 0x1c000
	ds_read_b128 v[132:135], v144
	ds_read_b128 v[154:157], v144 offset:1024
	ds_read_b128 v[158:161], v144 offset:2048
	ds_read_b128 v[162:165], v144 offset:3072
	v_add_u32_e32 v144, s43, v167
	ds_read_b128 v[172:175], v144
	ds_read_b128 v[176:179], v144 offset:1024
	ds_read_b128 v[180:183], v144 offset:2048
	ds_read_b128 v[184:187], v144 offset:3072
	s_add_u32 s46, s46, 0x80000
	s_addc_u32 s47, s47, 0
	s_mov_b32 m0, s44
	v_lshl_add_u64 v[228:229], s[46:47], 0, v[136:137]
	ds_read_b128 v[188:191], v171 offset:32768
	ds_read_b128 v[192:195], v171 offset:33792
	ds_read_b128 v[196:199], v171 offset:34816
	ds_read_b128 v[200:203], v171 offset:35840
	ds_read_b128 v[204:207], v171 offset:36864
	ds_read_b128 v[208:211], v171 offset:37888
	ds_read_b128 v[212:215], v171 offset:38912
	ds_read_b128 v[216:219], v171 offset:39936
	global_load_lds_dwordx4 v[228:229], off
	v_lshl_add_u64 v[228:229], s[46:47], 0, v[140:141]
	s_mov_b32 m0, s45
	s_nop 0
	global_load_lds_dwordx4 v[228:229], off
	s_waitcnt vmcnt(8)
	s_waitcnt lgkmcnt(0)
	s_barrier
	s_setprio 0
	s_waitcnt lgkmcnt(0)
	v_mfma_f32_16x16x32_bf16 v[124:127], v[132:135], v[188:191], v[124:127]
	v_mfma_f32_16x16x32_bf16 v[120:123], v[158:161], v[188:191], v[120:123]
	v_mfma_f32_16x16x32_bf16 v[108:111], v[132:135], v[196:199], v[108:111]
	v_mfma_f32_16x16x32_bf16 v[104:107], v[158:161], v[196:199], v[104:107]
	v_mfma_f32_16x16x32_bf16 v[92:95], v[132:135], v[204:207], v[92:95]
	v_mfma_f32_16x16x32_bf16 v[88:91], v[158:161], v[204:207], v[88:91]
	v_mfma_f32_16x16x32_bf16 v[76:79], v[132:135], v[212:215], v[76:79]
	v_mfma_f32_16x16x32_bf16 v[72:75], v[158:161], v[212:215], v[72:75]
	v_mfma_f32_16x16x32_bf16 v[124:127], v[154:157], v[192:195], v[124:127]
	v_mfma_f32_16x16x32_bf16 v[120:123], v[162:165], v[192:195], v[120:123]
	v_mfma_f32_16x16x32_bf16 v[108:111], v[154:157], v[200:203], v[108:111]
	v_mfma_f32_16x16x32_bf16 v[104:107], v[162:165], v[200:203], v[104:107]
	v_mfma_f32_16x16x32_bf16 v[92:95], v[154:157], v[208:211], v[92:95]
	v_mfma_f32_16x16x32_bf16 v[88:91], v[162:165], v[208:211], v[88:91]
	v_mfma_f32_16x16x32_bf16 v[76:79], v[154:157], v[216:219], v[76:79]
	v_mfma_f32_16x16x32_bf16 v[72:75], v[162:165], v[216:219], v[72:75]
	v_mfma_f32_16x16x32_bf16 v[116:119], v[172:175], v[188:191], v[116:119]
	v_mfma_f32_16x16x32_bf16 v[112:115], v[180:183], v[188:191], v[112:115]
	v_mfma_f32_16x16x32_bf16 v[100:103], v[172:175], v[196:199], v[100:103]
	v_mfma_f32_16x16x32_bf16 v[96:99], v[180:183], v[196:199], v[96:99]
	v_mfma_f32_16x16x32_bf16 v[84:87], v[172:175], v[204:207], v[84:87]
	v_mfma_f32_16x16x32_bf16 v[80:83], v[180:183], v[204:207], v[80:83]
	v_mfma_f32_16x16x32_bf16 v[68:71], v[172:175], v[212:215], v[68:71]
	v_mfma_f32_16x16x32_bf16 v[64:67], v[180:183], v[212:215], v[64:67]
	v_mfma_f32_16x16x32_bf16 v[116:119], v[176:179], v[192:195], v[116:119]
	v_mfma_f32_16x16x32_bf16 v[112:115], v[184:187], v[192:195], v[112:115]
	v_mfma_f32_16x16x32_bf16 v[100:103], v[176:179], v[200:203], v[100:103]
	v_mfma_f32_16x16x32_bf16 v[96:99], v[184:187], v[200:203], v[96:99]
	v_mfma_f32_16x16x32_bf16 v[84:87], v[176:179], v[208:211], v[84:87]
	v_mfma_f32_16x16x32_bf16 v[80:83], v[184:187], v[208:211], v[80:83]
	v_mfma_f32_16x16x32_bf16 v[68:71], v[176:179], v[216:219], v[68:71]
	v_mfma_f32_16x16x32_bf16 v[64:67], v[184:187], v[216:219], v[64:67]
	s_setprio 3
	s_barrier
	s_add_i32 s42, s42, s71
	v_lshl_add_u64 v[220:221], v[220:221], 0, s[34:35]
	s_mov_b32 m0, s42
	ds_read_b128 v[188:191], v171 offset:49152
	ds_read_b128 v[192:195], v171 offset:50176
	ds_read_b128 v[196:199], v171 offset:51200
	ds_read_b128 v[200:203], v171 offset:52224
	ds_read_b128 v[204:207], v171 offset:53248
	ds_read_b128 v[208:211], v171 offset:54272
	ds_read_b128 v[212:215], v171 offset:55296
	ds_read_b128 v[216:219], v171 offset:56320
	global_load_lds_dwordx4 v[220:221], off
	s_add_i32 m0, s42, 0x2000
	s_add_u32 s4, s4, 0x80080
	v_lshl_add_u64 v[220:221], v[222:223], 0, s[34:35]
	s_addc_u32 s5, s5, 0
	s_add_i32 s42, s43, s71
	global_load_lds_dwordx4 v[220:221], off
	v_lshl_add_u64 v[220:221], s[4:5], 0, v[138:139]
	s_mov_b32 m0, s42
	s_nop 0
	global_load_lds_dwordx4 v[220:221], off
	v_lshl_add_u64 v[220:221], s[4:5], 0, v[142:143]
	s_add_i32 m0, s42, 0x2000
	s_nop 0
	global_load_lds_dwordx4 v[220:221], off
	v_lshl_add_u64 v[220:221], v[224:225], 0, s[34:35]
	s_mov_b32 m0, s60
	s_nop 0
	global_load_lds_dwordx4 v[220:221], off
	v_lshl_add_u64 v[220:221], v[226:227], 0, s[34:35]
	s_mov_b32 m0, s61
	s_nop 0
	global_load_lds_dwordx4 v[220:221], off
	s_waitcnt vmcnt(8)
	s_waitcnt lgkmcnt(0)
	s_barrier
	s_setprio 0
	s_waitcnt lgkmcnt(0)
	v_mfma_f32_16x16x32_bf16 v[60:63], v[132:135], v[188:191], v[60:63]
	v_mfma_f32_16x16x32_bf16 v[56:59], v[158:161], v[188:191], v[56:59]
	v_mfma_f32_16x16x32_bf16 v[44:47], v[132:135], v[196:199], v[44:47]
	v_mfma_f32_16x16x32_bf16 v[40:43], v[158:161], v[196:199], v[40:43]
	v_mfma_f32_16x16x32_bf16 v[28:31], v[132:135], v[204:207], v[28:31]
	v_mfma_f32_16x16x32_bf16 v[24:27], v[158:161], v[204:207], v[24:27]
	v_mfma_f32_16x16x32_bf16 v[12:15], v[132:135], v[212:215], v[12:15]
	v_mfma_f32_16x16x32_bf16 v[8:11], v[158:161], v[212:215], v[8:11]
	v_mfma_f32_16x16x32_bf16 v[60:63], v[154:157], v[192:195], v[60:63]
	v_mfma_f32_16x16x32_bf16 v[56:59], v[162:165], v[192:195], v[56:59]
	v_mfma_f32_16x16x32_bf16 v[44:47], v[154:157], v[200:203], v[44:47]
	v_mfma_f32_16x16x32_bf16 v[40:43], v[162:165], v[200:203], v[40:43]
	v_mfma_f32_16x16x32_bf16 v[28:31], v[154:157], v[208:211], v[28:31]
	v_mfma_f32_16x16x32_bf16 v[24:27], v[162:165], v[208:211], v[24:27]
	v_mfma_f32_16x16x32_bf16 v[12:15], v[154:157], v[216:219], v[12:15]
	v_mfma_f32_16x16x32_bf16 v[8:11], v[162:165], v[216:219], v[8:11]
	v_mfma_f32_16x16x32_bf16 v[52:55], v[172:175], v[188:191], v[52:55]
	v_mfma_f32_16x16x32_bf16 v[48:51], v[180:183], v[188:191], v[48:51]
	v_mfma_f32_16x16x32_bf16 v[36:39], v[172:175], v[196:199], v[36:39]
	v_mfma_f32_16x16x32_bf16 v[32:35], v[180:183], v[196:199], v[32:35]
	v_mfma_f32_16x16x32_bf16 v[20:23], v[172:175], v[204:207], v[20:23]
	v_mfma_f32_16x16x32_bf16 v[16:19], v[180:183], v[204:207], v[16:19]
	v_mfma_f32_16x16x32_bf16 v[4:7], v[172:175], v[212:215], v[4:7]
	v_mfma_f32_16x16x32_bf16 v[0:3], v[180:183], v[212:215], v[0:3]
	v_mfma_f32_16x16x32_bf16 v[52:55], v[176:179], v[192:195], v[52:55]
	v_mfma_f32_16x16x32_bf16 v[48:51], v[184:187], v[192:195], v[48:51]
	v_mfma_f32_16x16x32_bf16 v[36:39], v[176:179], v[200:203], v[36:39]
	v_mfma_f32_16x16x32_bf16 v[32:35], v[184:187], v[200:203], v[32:35]
	v_mfma_f32_16x16x32_bf16 v[20:23], v[176:179], v[208:211], v[20:23]
	v_mfma_f32_16x16x32_bf16 v[16:19], v[184:187], v[208:211], v[16:19]
	v_mfma_f32_16x16x32_bf16 v[4:7], v[176:179], v[216:219], v[4:7]
	v_mfma_f32_16x16x32_bf16 v[0:3], v[184:187], v[216:219], v[0:3]
	s_setprio 3
	s_barrier
	s_add_i32 s85, s85, 2
	v_lshl_add_u64 v[128:129], v[128:129], 0, s[58:59]
	v_lshl_add_u64 v[130:131], v[130:131], 0, s[58:59]
	s_cbranch_vccz .LBB0_812
	s_and_b64 vcc, exec, s[50:51]
	s_cbranch_vccz .LBB0_815
	s_barrier

.LBB0_2230:
	s_add_i32 s66, s65, 2
	s_cmp_lt_u32 s65, 30
	s_cselect_b32 s42, 0, 0xffffffe0
	s_add_i32 s42, s66, s42
	s_ashr_i32 s43, s42, 31
	s_lshl_b64 s[42:43], s[42:43], 7
	s_add_u32 s46, s34, s42
	s_addc_u32 s47, s35, s43
	s_add_u32 s42, s30, s42
	s_addc_u32 s43, s31, s43
	s_cmp_eq_u32 s65, 30
	s_cselect_b32 s53, s23, s47
	s_cselect_b32 s52, s63, s46
	s_cselect_b32 s55, s21, s43
	s_cselect_b32 s54, s64, s42
	s_add_i32 s43, s60, s40
	ds_read_b128 v[154:157], v151
	ds_read_b128 v[158:161], v151 offset:1024
	ds_read_b128 v[162:165], v151 offset:2048
	ds_read_b128 v[166:169], v151 offset:3072
	ds_read_b128 v[170:173], v152
	ds_read_b128 v[174:177], v152 offset:1024
	ds_read_b128 v[178:181], v152 offset:2048
	ds_read_b128 v[182:185], v152 offset:3072
	s_add_i32 m0, s29, 0xc000
	s_add_i32 s42, s29, 0xe000
	s_add_i32 s71, s43, 0x2000
	s_add_u32 s56, s54, 0x80000
	s_addc_u32 s57, s55, 0
	s_add_i32 s72, s61, s40
	s_add_i32 s74, s72, 0x2000
	s_add_i32 s75, 0, 0x18000
	s_add_i32 s76, 0, 0x1c000
	s_add_u32 s50, s52, 0x80000
	s_addc_u32 s51, s53, 0
	s_add_i32 s68, s75, s40
	s_add_i32 s67, s68, 0x2000
	s_add_u32 s46, s54, 0x80080
	s_addc_u32 s47, s55, 0
	s_add_i32 s70, s76, s40
	s_add_i32 s69, s70, 0x2000
	s_cmp_gt_u32 s65, 29
	ds_read_b128 v[186:189], v153
	ds_read_b128 v[190:193], v153 offset:1024
	ds_read_b128 v[194:197], v153 offset:2048
	ds_read_b128 v[198:201], v153 offset:3072
	ds_read_b128 v[202:205], v153 offset:4096
	ds_read_b128 v[206:209], v153 offset:5120
	ds_read_b128 v[210:213], v153 offset:6144
	ds_read_b128 v[214:217], v153 offset:7168
	global_load_lds_dwordx4 v[144:145], off
	s_mov_b32 m0, s42
	s_nop 0
	global_load_lds_dwordx4 v[146:147], off
	s_waitcnt vmcnt(8)
	s_waitcnt lgkmcnt(0)
	s_barrier
	s_setprio 0
	s_waitcnt lgkmcnt(0)
	v_mfma_f32_16x16x32_bf16 v[124:127], v[154:157], v[186:189], v[124:127]
	v_mfma_f32_16x16x32_bf16 v[120:123], v[162:165], v[186:189], v[120:123]
	v_mfma_f32_16x16x32_bf16 v[116:119], v[154:157], v[194:197], v[116:119]
	v_mfma_f32_16x16x32_bf16 v[108:111], v[162:165], v[194:197], v[108:111]
	v_mfma_f32_16x16x32_bf16 v[100:103], v[154:157], v[202:205], v[100:103]
	v_mfma_f32_16x16x32_bf16 v[92:95], v[162:165], v[202:205], v[92:95]
	v_mfma_f32_16x16x32_bf16 v[84:87], v[154:157], v[210:213], v[84:87]
	v_mfma_f32_16x16x32_bf16 v[76:79], v[162:165], v[210:213], v[76:79]
	v_mfma_f32_16x16x32_bf16 v[124:127], v[158:161], v[190:193], v[124:127]
	v_mfma_f32_16x16x32_bf16 v[120:123], v[166:169], v[190:193], v[120:123]
	v_mfma_f32_16x16x32_bf16 v[116:119], v[158:161], v[198:201], v[116:119]
	v_mfma_f32_16x16x32_bf16 v[108:111], v[166:169], v[198:201], v[108:111]
	v_mfma_f32_16x16x32_bf16 v[100:103], v[158:161], v[206:209], v[100:103]
	v_mfma_f32_16x16x32_bf16 v[92:95], v[166:169], v[206:209], v[92:95]
	v_mfma_f32_16x16x32_bf16 v[84:87], v[158:161], v[214:217], v[84:87]
	v_mfma_f32_16x16x32_bf16 v[76:79], v[166:169], v[214:217], v[76:79]
	v_mfma_f32_16x16x32_bf16 v[112:115], v[170:173], v[186:189], v[112:115]
	v_mfma_f32_16x16x32_bf16 v[104:107], v[178:181], v[186:189], v[104:107]
	v_mfma_f32_16x16x32_bf16 v[96:99], v[170:173], v[194:197], v[96:99]
	v_mfma_f32_16x16x32_bf16 v[88:91], v[178:181], v[194:197], v[88:91]
	v_mfma_f32_16x16x32_bf16 v[80:83], v[170:173], v[202:205], v[80:83]
	v_mfma_f32_16x16x32_bf16 v[72:75], v[178:181], v[202:205], v[72:75]
	v_mfma_f32_16x16x32_bf16 v[68:71], v[170:173], v[210:213], v[68:71]
	v_mfma_f32_16x16x32_bf16 v[64:67], v[178:181], v[210:213], v[64:67]
	v_mfma_f32_16x16x32_bf16 v[112:115], v[174:177], v[190:193], v[112:115]
	v_mfma_f32_16x16x32_bf16 v[104:107], v[182:185], v[190:193], v[104:107]
	v_mfma_f32_16x16x32_bf16 v[96:99], v[174:177], v[198:201], v[96:99]
	v_mfma_f32_16x16x32_bf16 v[88:91], v[182:185], v[198:201], v[88:91]
	v_mfma_f32_16x16x32_bf16 v[80:83], v[174:177], v[206:209], v[80:83]
	v_mfma_f32_16x16x32_bf16 v[72:75], v[182:185], v[206:209], v[72:75]
	v_mfma_f32_16x16x32_bf16 v[68:71], v[174:177], v[214:217], v[68:71]
	v_mfma_f32_16x16x32_bf16 v[64:67], v[182:185], v[214:217], v[64:67]
	s_setprio 3
	s_barrier
	s_mov_b32 m0, s43
	v_lshl_add_u64 v[218:219], s[54:55], 0, v[130:131]
	ds_read_b128 v[186:189], v153 offset:16384
	ds_read_b128 v[190:193], v153 offset:17408
	ds_read_b128 v[194:197], v153 offset:18432
	ds_read_b128 v[198:201], v153 offset:19456
	ds_read_b128 v[202:205], v153 offset:20480
	ds_read_b128 v[206:209], v153 offset:21504
	ds_read_b128 v[210:213], v153 offset:22528
	ds_read_b128 v[214:217], v153 offset:23552
	global_load_lds_dwordx4 v[218:219], off
	v_lshl_add_u64 v[220:221], s[54:55], 0, v[134:135]
	s_mov_b32 m0, s71
	v_lshl_add_u64 v[222:223], s[56:57], 0, v[130:131]
	global_load_lds_dwordx4 v[220:221], off
	s_mov_b32 m0, s72
	v_lshl_add_u64 v[224:225], s[52:53], 0, v[132:133]
	global_load_lds_dwordx4 v[222:223], off
	v_lshl_add_u64 v[222:223], s[56:57], 0, v[134:135]
	s_mov_b32 m0, s74
	s_nop 0
	global_load_lds_dwordx4 v[222:223], off
	v_lshl_add_u64 v[222:223], s[52:53], 0, v[128:129]
	s_mov_b32 m0, s29
	s_nop 0
	global_load_lds_dwordx4 v[222:223], off
	s_mov_b32 m0, s41
	s_nop 0
	global_load_lds_dwordx4 v[224:225], off
	s_waitcnt vmcnt(8)
	s_waitcnt lgkmcnt(0)
	s_barrier
	s_setprio 0
	s_waitcnt lgkmcnt(0)
	v_mfma_f32_16x16x32_bf16 v[60:63], v[154:157], v[186:189], v[60:63]
	v_mfma_f32_16x16x32_bf16 v[56:59], v[162:165], v[186:189], v[56:59]
	v_mfma_f32_16x16x32_bf16 v[52:55], v[154:157], v[194:197], v[52:55]
	v_mfma_f32_16x16x32_bf16 v[44:47], v[162:165], v[194:197], v[44:47]
	v_mfma_f32_16x16x32_bf16 v[36:39], v[154:157], v[202:205], v[36:39]
	v_mfma_f32_16x16x32_bf16 v[28:31], v[162:165], v[202:205], v[28:31]
	v_mfma_f32_16x16x32_bf16 v[20:23], v[154:157], v[210:213], v[20:23]
	v_mfma_f32_16x16x32_bf16 v[12:15], v[162:165], v[210:213], v[12:15]
	v_mfma_f32_16x16x32_bf16 v[60:63], v[158:161], v[190:193], v[60:63]
	v_mfma_f32_16x16x32_bf16 v[56:59], v[166:169], v[190:193], v[56:59]
	v_mfma_f32_16x16x32_bf16 v[52:55], v[158:161], v[198:201], v[52:55]
	v_mfma_f32_16x16x32_bf16 v[44:47], v[166:169], v[198:201], v[44:47]
	v_mfma_f32_16x16x32_bf16 v[36:39], v[158:161], v[206:209], v[36:39]
	v_mfma_f32_16x16x32_bf16 v[28:31], v[166:169], v[206:209], v[28:31]
	v_mfma_f32_16x16x32_bf16 v[20:23], v[158:161], v[214:217], v[20:23]
	v_mfma_f32_16x16x32_bf16 v[12:15], v[166:169], v[214:217], v[12:15]
	v_mfma_f32_16x16x32_bf16 v[48:51], v[170:173], v[186:189], v[48:51]
	v_mfma_f32_16x16x32_bf16 v[40:43], v[178:181], v[186:189], v[40:43]
	v_mfma_f32_16x16x32_bf16 v[32:35], v[170:173], v[194:197], v[32:35]
	v_mfma_f32_16x16x32_bf16 v[24:27], v[178:181], v[194:197], v[24:27]
	v_mfma_f32_16x16x32_bf16 v[16:19], v[170:173], v[202:205], v[16:19]
	v_mfma_f32_16x16x32_bf16 v[8:11], v[178:181], v[202:205], v[8:11]
	v_mfma_f32_16x16x32_bf16 v[4:7], v[170:173], v[210:213], v[4:7]
	v_mfma_f32_16x16x32_bf16 v[0:3], v[178:181], v[210:213], v[0:3]
	v_mfma_f32_16x16x32_bf16 v[48:51], v[174:177], v[190:193], v[48:51]
	v_mfma_f32_16x16x32_bf16 v[40:43], v[182:185], v[190:193], v[40:43]
	v_mfma_f32_16x16x32_bf16 v[32:35], v[174:177], v[198:201], v[32:35]
	v_mfma_f32_16x16x32_bf16 v[24:27], v[182:185], v[198:201], v[24:27]
	v_mfma_f32_16x16x32_bf16 v[16:19], v[174:177], v[206:209], v[16:19]
	v_mfma_f32_16x16x32_bf16 v[8:11], v[182:185], v[206:209], v[8:11]
	v_mfma_f32_16x16x32_bf16 v[4:7], v[174:177], v[214:217], v[4:7]
	v_mfma_f32_16x16x32_bf16 v[0:3], v[182:185], v[214:217], v[0:3]
	s_setprio 3
	s_barrier
	v_add_u32_e32 v166, s75, v149
	v_add_u32_e32 v182, s76, v149
	ds_read_b128 v[154:157], v166
	ds_read_b128 v[158:161], v166 offset:1024
	ds_read_b128 v[162:165], v166 offset:2048
	ds_read_b128 v[166:169], v166 offset:3072
	ds_read_b128 v[170:173], v182
	ds_read_b128 v[174:177], v182 offset:1024
	ds_read_b128 v[178:181], v182 offset:2048
	ds_read_b128 v[182:185], v182 offset:3072
	s_mov_b32 m0, s44
	v_lshl_add_u64 v[226:227], s[50:51], 0, v[128:129]
	ds_read_b128 v[186:189], v153 offset:32768
	ds_read_b128 v[190:193], v153 offset:33792
	ds_read_b128 v[194:197], v153 offset:34816
	ds_read_b128 v[198:201], v153 offset:35840
	ds_read_b128 v[202:205], v153 offset:36864
	ds_read_b128 v[206:209], v153 offset:37888
	ds_read_b128 v[210:213], v153 offset:38912
	ds_read_b128 v[214:217], v153 offset:39936
	global_load_lds_dwordx4 v[226:227], off
	v_lshl_add_u64 v[226:227], s[50:51], 0, v[132:133]
	s_mov_b32 m0, s45
	s_nop 0
	global_load_lds_dwordx4 v[226:227], off
	s_waitcnt vmcnt(8)
	s_waitcnt lgkmcnt(0)
	s_barrier
	s_setprio 0
	s_waitcnt lgkmcnt(0)
	v_mfma_f32_16x16x32_bf16 v[124:127], v[154:157], v[186:189], v[124:127]
	v_mfma_f32_16x16x32_bf16 v[120:123], v[162:165], v[186:189], v[120:123]
	v_mfma_f32_16x16x32_bf16 v[116:119], v[154:157], v[194:197], v[116:119]
	v_mfma_f32_16x16x32_bf16 v[108:111], v[162:165], v[194:197], v[108:111]
	v_mfma_f32_16x16x32_bf16 v[100:103], v[154:157], v[202:205], v[100:103]
	v_mfma_f32_16x16x32_bf16 v[92:95], v[162:165], v[202:205], v[92:95]
	v_mfma_f32_16x16x32_bf16 v[84:87], v[154:157], v[210:213], v[84:87]
	v_mfma_f32_16x16x32_bf16 v[76:79], v[162:165], v[210:213], v[76:79]
	v_mfma_f32_16x16x32_bf16 v[124:127], v[158:161], v[190:193], v[124:127]
	v_mfma_f32_16x16x32_bf16 v[120:123], v[166:169], v[190:193], v[120:123]
	v_mfma_f32_16x16x32_bf16 v[116:119], v[158:161], v[198:201], v[116:119]
	v_mfma_f32_16x16x32_bf16 v[108:111], v[166:169], v[198:201], v[108:111]
	v_mfma_f32_16x16x32_bf16 v[100:103], v[158:161], v[206:209], v[100:103]
	v_mfma_f32_16x16x32_bf16 v[92:95], v[166:169], v[206:209], v[92:95]
	v_mfma_f32_16x16x32_bf16 v[84:87], v[158:161], v[214:217], v[84:87]
	v_mfma_f32_16x16x32_bf16 v[76:79], v[166:169], v[214:217], v[76:79]
	v_mfma_f32_16x16x32_bf16 v[112:115], v[170:173], v[186:189], v[112:115]
	v_mfma_f32_16x16x32_bf16 v[104:107], v[178:181], v[186:189], v[104:107]
	v_mfma_f32_16x16x32_bf16 v[96:99], v[170:173], v[194:197], v[96:99]
	v_mfma_f32_16x16x32_bf16 v[88:91], v[178:181], v[194:197], v[88:91]
	v_mfma_f32_16x16x32_bf16 v[80:83], v[170:173], v[202:205], v[80:83]
	v_mfma_f32_16x16x32_bf16 v[72:75], v[178:181], v[202:205], v[72:75]
	v_mfma_f32_16x16x32_bf16 v[68:71], v[170:173], v[210:213], v[68:71]
	v_mfma_f32_16x16x32_bf16 v[64:67], v[178:181], v[210:213], v[64:67]
	v_mfma_f32_16x16x32_bf16 v[112:115], v[174:177], v[190:193], v[112:115]
	v_mfma_f32_16x16x32_bf16 v[104:107], v[182:185], v[190:193], v[104:107]
	v_mfma_f32_16x16x32_bf16 v[96:99], v[174:177], v[198:201], v[96:99]
	v_mfma_f32_16x16x32_bf16 v[88:91], v[182:185], v[198:201], v[88:91]
	v_mfma_f32_16x16x32_bf16 v[80:83], v[174:177], v[206:209], v[80:83]
	v_mfma_f32_16x16x32_bf16 v[72:75], v[182:185], v[206:209], v[72:75]
	v_mfma_f32_16x16x32_bf16 v[68:71], v[174:177], v[214:217], v[68:71]
	v_mfma_f32_16x16x32_bf16 v[64:67], v[182:185], v[214:217], v[64:67]
	s_setprio 3
	s_barrier
	s_mov_b32 m0, s68
	v_lshl_add_u64 v[218:219], v[218:219], 0, s[14:15]
	ds_read_b128 v[186:189], v153 offset:49152
	ds_read_b128 v[190:193], v153 offset:50176
	ds_read_b128 v[194:197], v153 offset:51200
	ds_read_b128 v[198:201], v153 offset:52224
	ds_read_b128 v[202:205], v153 offset:53248
	ds_read_b128 v[206:209], v153 offset:54272
	ds_read_b128 v[210:213], v153 offset:55296
	ds_read_b128 v[214:217], v153 offset:56320
	global_load_lds_dwordx4 v[218:219], off
	v_lshl_add_u64 v[218:219], v[220:221], 0, s[14:15]
	s_mov_b32 m0, s67
	s_nop 0
	global_load_lds_dwordx4 v[218:219], off
	v_lshl_add_u64 v[218:219], s[46:47], 0, v[130:131]
	s_mov_b32 m0, s70
	s_nop 0
	global_load_lds_dwordx4 v[218:219], off
	v_lshl_add_u64 v[218:219], s[46:47], 0, v[134:135]
	s_mov_b32 m0, s69
	s_nop 0
	global_load_lds_dwordx4 v[218:219], off
	v_lshl_add_u64 v[218:219], v[222:223], 0, s[14:15]
	s_mov_b32 m0, s49
	s_nop 0
	global_load_lds_dwordx4 v[218:219], off
	v_lshl_add_u64 v[218:219], v[224:225], 0, s[14:15]
	s_mov_b32 m0, s58
	s_nop 0
	global_load_lds_dwordx4 v[218:219], off
	s_waitcnt vmcnt(8)
	s_waitcnt lgkmcnt(0)
	s_barrier
	s_setprio 0
	s_waitcnt lgkmcnt(0)
	v_mfma_f32_16x16x32_bf16 v[60:63], v[154:157], v[186:189], v[60:63]
	v_mfma_f32_16x16x32_bf16 v[56:59], v[162:165], v[186:189], v[56:59]
	v_mfma_f32_16x16x32_bf16 v[52:55], v[154:157], v[194:197], v[52:55]
	v_mfma_f32_16x16x32_bf16 v[44:47], v[162:165], v[194:197], v[44:47]
	v_mfma_f32_16x16x32_bf16 v[36:39], v[154:157], v[202:205], v[36:39]
	v_mfma_f32_16x16x32_bf16 v[28:31], v[162:165], v[202:205], v[28:31]
	v_mfma_f32_16x16x32_bf16 v[20:23], v[154:157], v[210:213], v[20:23]
	v_mfma_f32_16x16x32_bf16 v[12:15], v[162:165], v[210:213], v[12:15]
	v_mfma_f32_16x16x32_bf16 v[60:63], v[158:161], v[190:193], v[60:63]
	v_mfma_f32_16x16x32_bf16 v[56:59], v[166:169], v[190:193], v[56:59]
	v_mfma_f32_16x16x32_bf16 v[52:55], v[158:161], v[198:201], v[52:55]
	v_mfma_f32_16x16x32_bf16 v[44:47], v[166:169], v[198:201], v[44:47]
	v_mfma_f32_16x16x32_bf16 v[36:39], v[158:161], v[206:209], v[36:39]
	v_mfma_f32_16x16x32_bf16 v[28:31], v[166:169], v[206:209], v[28:31]
	v_mfma_f32_16x16x32_bf16 v[20:23], v[158:161], v[214:217], v[20:23]
	v_mfma_f32_16x16x32_bf16 v[12:15], v[166:169], v[214:217], v[12:15]
	v_mfma_f32_16x16x32_bf16 v[48:51], v[170:173], v[186:189], v[48:51]
	v_mfma_f32_16x16x32_bf16 v[40:43], v[178:181], v[186:189], v[40:43]
	v_mfma_f32_16x16x32_bf16 v[32:35], v[170:173], v[194:197], v[32:35]
	v_mfma_f32_16x16x32_bf16 v[24:27], v[178:181], v[194:197], v[24:27]
	v_mfma_f32_16x16x32_bf16 v[16:19], v[170:173], v[202:205], v[16:19]
	v_mfma_f32_16x16x32_bf16 v[8:11], v[178:181], v[202:205], v[8:11]
	v_mfma_f32_16x16x32_bf16 v[4:7], v[170:173], v[210:213], v[4:7]
	v_mfma_f32_16x16x32_bf16 v[0:3], v[178:181], v[210:213], v[0:3]
	v_mfma_f32_16x16x32_bf16 v[48:51], v[174:177], v[190:193], v[48:51]
	v_mfma_f32_16x16x32_bf16 v[40:43], v[182:185], v[190:193], v[40:43]
	v_mfma_f32_16x16x32_bf16 v[32:35], v[174:177], v[198:201], v[32:35]
	v_mfma_f32_16x16x32_bf16 v[24:27], v[182:185], v[198:201], v[24:27]
	v_mfma_f32_16x16x32_bf16 v[16:19], v[174:177], v[206:209], v[16:19]
	v_mfma_f32_16x16x32_bf16 v[8:11], v[182:185], v[206:209], v[8:11]
	v_mfma_f32_16x16x32_bf16 v[4:7], v[174:177], v[214:217], v[4:7]
	v_mfma_f32_16x16x32_bf16 v[0:3], v[182:185], v[214:217], v[0:3]
	s_setprio 3
	s_barrier
	v_lshl_add_u64 v[144:145], v[144:145], 0, s[18:19]
	v_lshl_add_u64 v[146:147], v[146:147], 0, s[18:19]
	s_mov_b32 s65, s66
	s_cbranch_scc0 .LBB0_2230
	s_and_b64 vcc, exec, s[16:17]
	s_cbranch_vccz .LBB0_2233
	s_barrier

.LBB0_2375:
	s_cmp_gt_u32 s63, 29
	s_cselect_b64 s[42:43], -1, 0
	ds_read_b128 v[160:163], v156
	ds_read_b128 v[164:167], v156 offset:1024
	ds_read_b128 v[168:171], v156 offset:2048
	ds_read_b128 v[172:175], v156 offset:3072
	ds_read_b128 v[176:179], v157
	ds_read_b128 v[180:183], v157 offset:1024
	ds_read_b128 v[184:187], v157 offset:2048
	ds_read_b128 v[188:191], v157 offset:3072
	s_and_b64 vcc, s[42:43], exec
	s_cselect_b32 s42, 0xffffffe2, 2
	s_add_i32 s42, s42, s63
	s_ashr_i32 s43, s42, 31
	s_lshl_b64 s[42:43], s[42:43], 7
	s_add_u32 s46, s50, s42
	s_addc_u32 s47, s51, s43
	s_add_u32 s42, s34, s42
	s_addc_u32 s43, s35, s43
	s_cmp_eq_u32 s63, 30
	s_cselect_b32 s53, s25, s47
	s_cselect_b32 s52, s61, s46
	s_cselect_b32 s47, s23, s43
	s_cselect_b32 s46, s62, s42
	s_add_i32 m0, s31, 0xc000
	ds_read_b128 v[192:195], v158
	ds_read_b128 v[196:199], v158 offset:1024
	ds_read_b128 v[200:203], v158 offset:2048
	ds_read_b128 v[204:207], v158 offset:3072
	ds_read_b128 v[208:211], v158 offset:4096
	ds_read_b128 v[212:215], v158 offset:5120
	ds_read_b128 v[216:219], v158 offset:6144
	ds_read_b128 v[220:223], v158 offset:7168
	global_load_lds_dwordx4 v[144:145], off
	s_add_i32 m0, s31, 0xe000
	s_nop 0
	global_load_lds_dwordx4 v[146:147], off
	s_waitcnt vmcnt(8)
	s_waitcnt lgkmcnt(0)
	s_barrier
	s_setprio 0
	s_waitcnt lgkmcnt(0)
	v_mfma_f32_16x16x32_bf16 v[124:127], v[160:163], v[192:195], v[124:127]
	v_mfma_f32_16x16x32_bf16 v[120:123], v[168:171], v[192:195], v[120:123]
	v_mfma_f32_16x16x32_bf16 v[108:111], v[160:163], v[200:203], v[108:111]
	v_mfma_f32_16x16x32_bf16 v[104:107], v[168:171], v[200:203], v[104:107]
	v_mfma_f32_16x16x32_bf16 v[92:95], v[160:163], v[208:211], v[92:95]
	v_mfma_f32_16x16x32_bf16 v[88:91], v[168:171], v[208:211], v[88:91]
	v_mfma_f32_16x16x32_bf16 v[76:79], v[160:163], v[216:219], v[76:79]
	v_mfma_f32_16x16x32_bf16 v[72:75], v[168:171], v[216:219], v[72:75]
	v_mfma_f32_16x16x32_bf16 v[124:127], v[164:167], v[196:199], v[124:127]
	v_mfma_f32_16x16x32_bf16 v[120:123], v[172:175], v[196:199], v[120:123]
	v_mfma_f32_16x16x32_bf16 v[108:111], v[164:167], v[204:207], v[108:111]
	v_mfma_f32_16x16x32_bf16 v[104:107], v[172:175], v[204:207], v[104:107]
	v_mfma_f32_16x16x32_bf16 v[92:95], v[164:167], v[212:215], v[92:95]
	v_mfma_f32_16x16x32_bf16 v[88:91], v[172:175], v[212:215], v[88:91]
	v_mfma_f32_16x16x32_bf16 v[76:79], v[164:167], v[220:223], v[76:79]
	v_mfma_f32_16x16x32_bf16 v[72:75], v[172:175], v[220:223], v[72:75]
	v_mfma_f32_16x16x32_bf16 v[116:119], v[176:179], v[192:195], v[116:119]
	v_mfma_f32_16x16x32_bf16 v[112:115], v[184:187], v[192:195], v[112:115]
	v_mfma_f32_16x16x32_bf16 v[100:103], v[176:179], v[200:203], v[100:103]
	v_mfma_f32_16x16x32_bf16 v[96:99], v[184:187], v[200:203], v[96:99]
	v_mfma_f32_16x16x32_bf16 v[84:87], v[176:179], v[208:211], v[84:87]
	v_mfma_f32_16x16x32_bf16 v[80:83], v[184:187], v[208:211], v[80:83]
	v_mfma_f32_16x16x32_bf16 v[68:71], v[176:179], v[216:219], v[68:71]
	v_mfma_f32_16x16x32_bf16 v[64:67], v[184:187], v[216:219], v[64:67]
	v_mfma_f32_16x16x32_bf16 v[116:119], v[180:183], v[196:199], v[116:119]
	v_mfma_f32_16x16x32_bf16 v[112:115], v[188:191], v[196:199], v[112:115]
	v_mfma_f32_16x16x32_bf16 v[100:103], v[180:183], v[204:207], v[100:103]
	v_mfma_f32_16x16x32_bf16 v[96:99], v[188:191], v[204:207], v[96:99]
	v_mfma_f32_16x16x32_bf16 v[84:87], v[180:183], v[212:215], v[84:87]
	v_mfma_f32_16x16x32_bf16 v[80:83], v[188:191], v[212:215], v[80:83]
	v_mfma_f32_16x16x32_bf16 v[68:71], v[180:183], v[220:223], v[68:71]
	v_mfma_f32_16x16x32_bf16 v[64:67], v[188:191], v[220:223], v[64:67]
	s_setprio 3
	s_barrier
	s_add_i32 s42, s57, s39
	v_lshl_add_u64 v[148:149], s[46:47], 0, v[132:133]
	s_mov_b32 m0, s42
	ds_read_b128 v[192:195], v158 offset:16384
	ds_read_b128 v[196:199], v158 offset:17408
	ds_read_b128 v[200:203], v158 offset:18432
	ds_read_b128 v[204:207], v158 offset:19456
	ds_read_b128 v[208:211], v158 offset:20480
	ds_read_b128 v[212:215], v158 offset:21504
	ds_read_b128 v[216:219], v158 offset:22528
	ds_read_b128 v[220:223], v158 offset:23552
	global_load_lds_dwordx4 v[148:149], off
	s_add_i32 m0, s42, 0x2000
	s_add_u32 s42, s46, 0x80000
	v_lshl_add_u64 v[224:225], s[46:47], 0, v[128:129]
	s_addc_u32 s43, s47, 0
	s_add_i32 s64, s58, s39
	global_load_lds_dwordx4 v[224:225], off
	v_lshl_add_u64 v[226:227], s[42:43], 0, v[132:133]
	s_mov_b32 m0, s64
	v_lshl_add_u64 v[228:229], s[52:53], 0, v[130:131]
	global_load_lds_dwordx4 v[226:227], off
	v_lshl_add_u64 v[226:227], s[42:43], 0, v[128:129]
	s_add_i32 m0, s64, 0x2000
	s_nop 0
	global_load_lds_dwordx4 v[226:227], off
	v_lshl_add_u64 v[226:227], s[52:53], 0, v[134:135]
	s_mov_b32 m0, s31
	s_nop 0
	global_load_lds_dwordx4 v[226:227], off
	s_mov_b32 m0, s44
	s_nop 0
	global_load_lds_dwordx4 v[228:229], off
	s_waitcnt vmcnt(8)
	s_waitcnt lgkmcnt(0)
	s_barrier
	s_setprio 0
	s_waitcnt lgkmcnt(0)
	v_mfma_f32_16x16x32_bf16 v[60:63], v[160:163], v[192:195], v[60:63]
	v_mfma_f32_16x16x32_bf16 v[56:59], v[168:171], v[192:195], v[56:59]
	v_mfma_f32_16x16x32_bf16 v[44:47], v[160:163], v[200:203], v[44:47]
	v_mfma_f32_16x16x32_bf16 v[40:43], v[168:171], v[200:203], v[40:43]
	v_mfma_f32_16x16x32_bf16 v[28:31], v[160:163], v[208:211], v[28:31]
	v_mfma_f32_16x16x32_bf16 v[24:27], v[168:171], v[208:211], v[24:27]
	v_mfma_f32_16x16x32_bf16 v[12:15], v[160:163], v[216:219], v[12:15]
	v_mfma_f32_16x16x32_bf16 v[8:11], v[168:171], v[216:219], v[8:11]
	v_mfma_f32_16x16x32_bf16 v[60:63], v[164:167], v[196:199], v[60:63]
	v_mfma_f32_16x16x32_bf16 v[56:59], v[172:175], v[196:199], v[56:59]
	v_mfma_f32_16x16x32_bf16 v[44:47], v[164:167], v[204:207], v[44:47]
	v_mfma_f32_16x16x32_bf16 v[40:43], v[172:175], v[204:207], v[40:43]
	v_mfma_f32_16x16x32_bf16 v[28:31], v[164:167], v[212:215], v[28:31]
	v_mfma_f32_16x16x32_bf16 v[24:27], v[172:175], v[212:215], v[24:27]
	v_mfma_f32_16x16x32_bf16 v[12:15], v[164:167], v[220:223], v[12:15]
	v_mfma_f32_16x16x32_bf16 v[8:11], v[172:175], v[220:223], v[8:11]
	v_mfma_f32_16x16x32_bf16 v[52:55], v[176:179], v[192:195], v[52:55]
	v_mfma_f32_16x16x32_bf16 v[48:51], v[184:187], v[192:195], v[48:51]
	v_mfma_f32_16x16x32_bf16 v[36:39], v[176:179], v[200:203], v[36:39]
	v_mfma_f32_16x16x32_bf16 v[32:35], v[184:187], v[200:203], v[32:35]
	v_mfma_f32_16x16x32_bf16 v[20:23], v[176:179], v[208:211], v[20:23]
	v_mfma_f32_16x16x32_bf16 v[16:19], v[184:187], v[208:211], v[16:19]
	v_mfma_f32_16x16x32_bf16 v[4:7], v[176:179], v[216:219], v[4:7]
	v_mfma_f32_16x16x32_bf16 v[0:3], v[184:187], v[216:219], v[0:3]
	v_mfma_f32_16x16x32_bf16 v[52:55], v[180:183], v[196:199], v[52:55]
	v_mfma_f32_16x16x32_bf16 v[48:51], v[188:191], v[196:199], v[48:51]
	v_mfma_f32_16x16x32_bf16 v[36:39], v[180:183], v[204:207], v[36:39]
	v_mfma_f32_16x16x32_bf16 v[32:35], v[188:191], v[204:207], v[32:35]
	v_mfma_f32_16x16x32_bf16 v[20:23], v[180:183], v[212:215], v[20:23]
	v_mfma_f32_16x16x32_bf16 v[16:19], v[188:191], v[212:215], v[16:19]
	v_mfma_f32_16x16x32_bf16 v[4:7], v[180:183], v[220:223], v[4:7]
	v_mfma_f32_16x16x32_bf16 v[0:3], v[188:191], v[220:223], v[0:3]
	s_setprio 3
	s_barrier
	s_add_i32 s64, 0, 0x18000
	v_add_u32_e32 v159, s64, v151
	s_add_i32 s65, 0, 0x1c000
	ds_read_b128 v[160:163], v159
	ds_read_b128 v[164:167], v159 offset:1024
	ds_read_b128 v[168:171], v159 offset:2048
	ds_read_b128 v[172:175], v159 offset:3072
	v_add_u32_e32 v159, s65, v151
	ds_read_b128 v[176:179], v159
	ds_read_b128 v[180:183], v159 offset:1024
	ds_read_b128 v[184:187], v159 offset:2048
	ds_read_b128 v[188:191], v159 offset:3072
	s_add_u32 s42, s52, 0x80000
	s_addc_u32 s43, s53, 0
	s_mov_b32 m0, s45
	v_lshl_add_u64 v[230:231], s[42:43], 0, v[134:135]
	ds_read_b128 v[192:195], v158 offset:32768
	ds_read_b128 v[196:199], v158 offset:33792
	ds_read_b128 v[200:203], v158 offset:34816
	ds_read_b128 v[204:207], v158 offset:35840
	ds_read_b128 v[208:211], v158 offset:36864
	ds_read_b128 v[212:215], v158 offset:37888
	ds_read_b128 v[216:219], v158 offset:38912
	ds_read_b128 v[220:223], v158 offset:39936
	global_load_lds_dwordx4 v[230:231], off
	v_lshl_add_u64 v[230:231], s[42:43], 0, v[130:131]
	s_mov_b32 m0, s48
	s_nop 0
	global_load_lds_dwordx4 v[230:231], off
	s_waitcnt vmcnt(8)
	s_waitcnt lgkmcnt(0)
	s_barrier
	s_setprio 0
	s_waitcnt lgkmcnt(0)
	v_mfma_f32_16x16x32_bf16 v[124:127], v[160:163], v[192:195], v[124:127]
	v_mfma_f32_16x16x32_bf16 v[120:123], v[168:171], v[192:195], v[120:123]
	v_mfma_f32_16x16x32_bf16 v[108:111], v[160:163], v[200:203], v[108:111]
	v_mfma_f32_16x16x32_bf16 v[104:107], v[168:171], v[200:203], v[104:107]
	v_mfma_f32_16x16x32_bf16 v[92:95], v[160:163], v[208:211], v[92:95]
	v_mfma_f32_16x16x32_bf16 v[88:91], v[168:171], v[208:211], v[88:91]
	v_mfma_f32_16x16x32_bf16 v[76:79], v[160:163], v[216:219], v[76:79]
	v_mfma_f32_16x16x32_bf16 v[72:75], v[168:171], v[216:219], v[72:75]
	v_mfma_f32_16x16x32_bf16 v[124:127], v[164:167], v[196:199], v[124:127]
	v_mfma_f32_16x16x32_bf16 v[120:123], v[172:175], v[196:199], v[120:123]
	v_mfma_f32_16x16x32_bf16 v[108:111], v[164:167], v[204:207], v[108:111]
	v_mfma_f32_16x16x32_bf16 v[104:107], v[172:175], v[204:207], v[104:107]
	v_mfma_f32_16x16x32_bf16 v[92:95], v[164:167], v[212:215], v[92:95]
	v_mfma_f32_16x16x32_bf16 v[88:91], v[172:175], v[212:215], v[88:91]
	v_mfma_f32_16x16x32_bf16 v[76:79], v[164:167], v[220:223], v[76:79]
	v_mfma_f32_16x16x32_bf16 v[72:75], v[172:175], v[220:223], v[72:75]
	v_mfma_f32_16x16x32_bf16 v[116:119], v[176:179], v[192:195], v[116:119]
	v_mfma_f32_16x16x32_bf16 v[112:115], v[184:187], v[192:195], v[112:115]
	v_mfma_f32_16x16x32_bf16 v[100:103], v[176:179], v[200:203], v[100:103]
	v_mfma_f32_16x16x32_bf16 v[96:99], v[184:187], v[200:203], v[96:99]
	v_mfma_f32_16x16x32_bf16 v[84:87], v[176:179], v[208:211], v[84:87]
	v_mfma_f32_16x16x32_bf16 v[80:83], v[184:187], v[208:211], v[80:83]
	v_mfma_f32_16x16x32_bf16 v[68:71], v[176:179], v[216:219], v[68:71]
	v_mfma_f32_16x16x32_bf16 v[64:67], v[184:187], v[216:219], v[64:67]
	v_mfma_f32_16x16x32_bf16 v[116:119], v[180:183], v[196:199], v[116:119]
	v_mfma_f32_16x16x32_bf16 v[112:115], v[188:191], v[196:199], v[112:115]
	v_mfma_f32_16x16x32_bf16 v[100:103], v[180:183], v[204:207], v[100:103]
	v_mfma_f32_16x16x32_bf16 v[96:99], v[188:191], v[204:207], v[96:99]
	v_mfma_f32_16x16x32_bf16 v[84:87], v[180:183], v[212:215], v[84:87]
	v_mfma_f32_16x16x32_bf16 v[80:83], v[188:191], v[212:215], v[80:83]
	v_mfma_f32_16x16x32_bf16 v[68:71], v[180:183], v[220:223], v[68:71]
	v_mfma_f32_16x16x32_bf16 v[64:67], v[188:191], v[220:223], v[64:67]
	s_setprio 3
	s_barrier
	s_add_i32 s42, s64, s39
	v_lshl_add_u64 v[148:149], v[148:149], 0, s[16:17]
	s_mov_b32 m0, s42
	ds_read_b128 v[192:195], v158 offset:49152
	ds_read_b128 v[196:199], v158 offset:50176
	ds_read_b128 v[200:203], v158 offset:51200
	ds_read_b128 v[204:207], v158 offset:52224
	ds_read_b128 v[208:211], v158 offset:53248
	ds_read_b128 v[212:215], v158 offset:54272
	ds_read_b128 v[216:219], v158 offset:55296
	ds_read_b128 v[220:223], v158 offset:56320
	global_load_lds_dwordx4 v[148:149], off
	s_add_i32 m0, s42, 0x2000
	s_add_u32 s42, s46, 0x80080
	v_lshl_add_u64 v[148:149], v[224:225], 0, s[16:17]
	s_addc_u32 s43, s47, 0
	s_add_i32 s46, s65, s39
	global_load_lds_dwordx4 v[148:149], off
	v_lshl_add_u64 v[148:149], s[42:43], 0, v[132:133]
	s_mov_b32 m0, s46
	s_nop 0
	global_load_lds_dwordx4 v[148:149], off
	v_lshl_add_u64 v[148:149], s[42:43], 0, v[128:129]
	s_add_i32 m0, s46, 0x2000
	s_nop 0
	global_load_lds_dwordx4 v[148:149], off
	v_lshl_add_u64 v[148:149], v[226:227], 0, s[16:17]
	s_mov_b32 m0, s49
	s_nop 0
	global_load_lds_dwordx4 v[148:149], off
	v_lshl_add_u64 v[148:149], v[228:229], 0, s[16:17]
	s_mov_b32 m0, s54
	s_nop 0
	global_load_lds_dwordx4 v[148:149], off
	s_waitcnt vmcnt(8)
	s_waitcnt lgkmcnt(0)
	s_barrier
	s_setprio 0
	s_waitcnt lgkmcnt(0)
	v_mfma_f32_16x16x32_bf16 v[60:63], v[160:163], v[192:195], v[60:63]
	v_mfma_f32_16x16x32_bf16 v[56:59], v[168:171], v[192:195], v[56:59]
	v_mfma_f32_16x16x32_bf16 v[44:47], v[160:163], v[200:203], v[44:47]
	v_mfma_f32_16x16x32_bf16 v[40:43], v[168:171], v[200:203], v[40:43]
	v_mfma_f32_16x16x32_bf16 v[28:31], v[160:163], v[208:211], v[28:31]
	v_mfma_f32_16x16x32_bf16 v[24:27], v[168:171], v[208:211], v[24:27]
	v_mfma_f32_16x16x32_bf16 v[12:15], v[160:163], v[216:219], v[12:15]
	v_mfma_f32_16x16x32_bf16 v[8:11], v[168:171], v[216:219], v[8:11]
	v_mfma_f32_16x16x32_bf16 v[60:63], v[164:167], v[196:199], v[60:63]
	v_mfma_f32_16x16x32_bf16 v[56:59], v[172:175], v[196:199], v[56:59]
	v_mfma_f32_16x16x32_bf16 v[44:47], v[164:167], v[204:207], v[44:47]
	v_mfma_f32_16x16x32_bf16 v[40:43], v[172:175], v[204:207], v[40:43]
	v_mfma_f32_16x16x32_bf16 v[28:31], v[164:167], v[212:215], v[28:31]
	v_mfma_f32_16x16x32_bf16 v[24:27], v[172:175], v[212:215], v[24:27]
	v_mfma_f32_16x16x32_bf16 v[12:15], v[164:167], v[220:223], v[12:15]
	v_mfma_f32_16x16x32_bf16 v[8:11], v[172:175], v[220:223], v[8:11]
	v_mfma_f32_16x16x32_bf16 v[52:55], v[176:179], v[192:195], v[52:55]
	v_mfma_f32_16x16x32_bf16 v[48:51], v[184:187], v[192:195], v[48:51]
	v_mfma_f32_16x16x32_bf16 v[36:39], v[176:179], v[200:203], v[36:39]
	v_mfma_f32_16x16x32_bf16 v[32:35], v[184:187], v[200:203], v[32:35]
	v_mfma_f32_16x16x32_bf16 v[20:23], v[176:179], v[208:211], v[20:23]
	v_mfma_f32_16x16x32_bf16 v[16:19], v[184:187], v[208:211], v[16:19]
	v_mfma_f32_16x16x32_bf16 v[4:7], v[176:179], v[216:219], v[4:7]
	v_mfma_f32_16x16x32_bf16 v[0:3], v[184:187], v[216:219], v[0:3]
	v_mfma_f32_16x16x32_bf16 v[52:55], v[180:183], v[196:199], v[52:55]
	v_mfma_f32_16x16x32_bf16 v[48:51], v[188:191], v[196:199], v[48:51]
	v_mfma_f32_16x16x32_bf16 v[36:39], v[180:183], v[204:207], v[36:39]
	v_mfma_f32_16x16x32_bf16 v[32:35], v[188:191], v[204:207], v[32:35]
	v_mfma_f32_16x16x32_bf16 v[20:23], v[180:183], v[212:215], v[20:23]
	v_mfma_f32_16x16x32_bf16 v[16:19], v[188:191], v[212:215], v[16:19]
	v_mfma_f32_16x16x32_bf16 v[4:7], v[180:183], v[220:223], v[4:7]
	v_mfma_f32_16x16x32_bf16 v[0:3], v[188:191], v[220:223], v[0:3]
	s_setprio 3
	s_barrier
	s_add_i32 s63, s63, 2
	v_lshl_add_u64 v[144:145], v[144:145], 0, s[20:21]
	v_lshl_add_u64 v[146:147], v[146:147], 0, s[20:21]
	s_cbranch_vccz .LBB0_2375
	s_and_b64 vcc, exec, s[18:19]
	s_cbranch_vccz .LBB0_2378
	s_barrier

.LBB0_2466:
	s_add_i32 s26, s34, s61
	s_cmpk_lt_u32 s26, 0x58
	s_cselect_b32 s27, 0, 0xffffffa8
	s_add_i32 s28, s26, s27
	s_cmpk_lt_i32 s28, 0x56
	s_cselect_b32 s29, 0, 0xffffffa8
	ds_read_b128 v[140:143], v147
	ds_read_b128 v[150:153], v147 offset:1024
	ds_read_b128 v[154:157], v147 offset:2048
	ds_read_b128 v[158:161], v147 offset:3072
	ds_read_b128 v[162:165], v148
	ds_read_b128 v[166:169], v148 offset:1024
	ds_read_b128 v[170:173], v148 offset:2048
	ds_read_b128 v[174:177], v148 offset:3072
	s_add_i32 s27, s27, s29
	s_add_i32 s26, s26, s27
	s_add_i32 s26, s26, 2
	s_add_i32 s42, s28, 1
	s_ashr_i32 s27, s26, 31
	s_ashr_i32 s43, s42, 31
	s_lshl_b64 s[26:27], s[26:27], 7
	s_add_u32 s28, s24, s26
	s_addc_u32 s29, s25, s27
	s_add_u32 s26, s22, s26
	s_addc_u32 s27, s23, s27
	s_cmpk_eq_i32 s61, 0x56
	s_cselect_b32 s29, s58, s29
	s_cselect_b32 s28, s57, s28
	s_cselect_b32 s27, s60, s27
	s_cselect_b32 s26, s59, s26
	s_lshl_b64 s[42:43], s[42:43], 7
	s_add_u32 s42, s55, s42
	s_addc_u32 s43, s56, s43
	v_lshl_add_u64 v[210:211], s[42:43], 0, v[128:129]
	s_add_i32 m0, s39, 0xc000
	ds_read_b128 v[178:181], v149
	ds_read_b128 v[182:185], v149 offset:1024
	ds_read_b128 v[186:189], v149 offset:2048
	ds_read_b128 v[190:193], v149 offset:3072
	ds_read_b128 v[194:197], v149 offset:4096
	ds_read_b128 v[198:201], v149 offset:5120
	ds_read_b128 v[202:205], v149 offset:6144
	ds_read_b128 v[206:209], v149 offset:7168
	global_load_lds_dwordx4 v[210:211], off
	v_lshl_add_u64 v[210:211], s[42:43], 0, v[132:133]
	s_add_i32 m0, s39, 0xe000
	s_nop 0
	global_load_lds_dwordx4 v[210:211], off
	s_waitcnt vmcnt(8)
	s_waitcnt lgkmcnt(0)
	s_barrier
	s_setprio 0
	s_waitcnt lgkmcnt(0)
	v_mfma_f32_16x16x32_bf16 v[124:127], v[140:143], v[178:181], v[124:127]
	v_mfma_f32_16x16x32_bf16 v[120:123], v[154:157], v[178:181], v[120:123]
	v_mfma_f32_16x16x32_bf16 v[116:119], v[140:143], v[186:189], v[116:119]
	v_mfma_f32_16x16x32_bf16 v[108:111], v[154:157], v[186:189], v[108:111]
	v_mfma_f32_16x16x32_bf16 v[100:103], v[140:143], v[194:197], v[100:103]
	v_mfma_f32_16x16x32_bf16 v[92:95], v[154:157], v[194:197], v[92:95]
	v_mfma_f32_16x16x32_bf16 v[84:87], v[140:143], v[202:205], v[84:87]
	v_mfma_f32_16x16x32_bf16 v[76:79], v[154:157], v[202:205], v[76:79]
	v_mfma_f32_16x16x32_bf16 v[124:127], v[150:153], v[182:185], v[124:127]
	v_mfma_f32_16x16x32_bf16 v[120:123], v[158:161], v[182:185], v[120:123]
	v_mfma_f32_16x16x32_bf16 v[116:119], v[150:153], v[190:193], v[116:119]
	v_mfma_f32_16x16x32_bf16 v[108:111], v[158:161], v[190:193], v[108:111]
	v_mfma_f32_16x16x32_bf16 v[100:103], v[150:153], v[198:201], v[100:103]
	v_mfma_f32_16x16x32_bf16 v[92:95], v[158:161], v[198:201], v[92:95]
	v_mfma_f32_16x16x32_bf16 v[84:87], v[150:153], v[206:209], v[84:87]
	v_mfma_f32_16x16x32_bf16 v[76:79], v[158:161], v[206:209], v[76:79]
	v_mfma_f32_16x16x32_bf16 v[112:115], v[162:165], v[178:181], v[112:115]
	v_mfma_f32_16x16x32_bf16 v[104:107], v[170:173], v[178:181], v[104:107]
	v_mfma_f32_16x16x32_bf16 v[96:99], v[162:165], v[186:189], v[96:99]
	v_mfma_f32_16x16x32_bf16 v[88:91], v[170:173], v[186:189], v[88:91]
	v_mfma_f32_16x16x32_bf16 v[80:83], v[162:165], v[194:197], v[80:83]
	v_mfma_f32_16x16x32_bf16 v[72:75], v[170:173], v[194:197], v[72:75]
	v_mfma_f32_16x16x32_bf16 v[68:71], v[162:165], v[202:205], v[68:71]
	v_mfma_f32_16x16x32_bf16 v[64:67], v[170:173], v[202:205], v[64:67]
	v_mfma_f32_16x16x32_bf16 v[112:115], v[166:169], v[182:185], v[112:115]
	v_mfma_f32_16x16x32_bf16 v[104:107], v[174:177], v[182:185], v[104:107]
	v_mfma_f32_16x16x32_bf16 v[96:99], v[166:169], v[190:193], v[96:99]
	v_mfma_f32_16x16x32_bf16 v[88:91], v[174:177], v[190:193], v[88:91]
	v_mfma_f32_16x16x32_bf16 v[80:83], v[166:169], v[198:201], v[80:83]
	v_mfma_f32_16x16x32_bf16 v[72:75], v[174:177], v[198:201], v[72:75]
	v_mfma_f32_16x16x32_bf16 v[68:71], v[166:169], v[206:209], v[68:71]
	v_mfma_f32_16x16x32_bf16 v[64:67], v[174:177], v[206:209], v[64:67]
	s_setprio 3
	s_barrier
	s_add_i32 s42, s49, s35
	v_lshl_add_u64 v[210:211], s[26:27], 0, v[130:131]
	s_mov_b32 m0, s42
	ds_read_b128 v[178:181], v149 offset:16384
	ds_read_b128 v[182:185], v149 offset:17408
	ds_read_b128 v[186:189], v149 offset:18432
	ds_read_b128 v[190:193], v149 offset:19456
	ds_read_b128 v[194:197], v149 offset:20480
	ds_read_b128 v[198:201], v149 offset:21504
	ds_read_b128 v[202:205], v149 offset:22528
	ds_read_b128 v[206:209], v149 offset:23552
	global_load_lds_dwordx4 v[210:211], off
	s_add_i32 m0, s42, 0x2000
	s_add_u32 s42, s26, 0x160000
	v_lshl_add_u64 v[212:213], s[26:27], 0, v[134:135]
	s_addc_u32 s43, s27, 0
	s_add_i32 s62, s50, s35
	global_load_lds_dwordx4 v[212:213], off
	v_lshl_add_u64 v[214:215], s[42:43], 0, v[130:131]
	s_mov_b32 m0, s62
	v_lshl_add_u64 v[216:217], s[28:29], 0, v[132:133]
	global_load_lds_dwordx4 v[214:215], off
	v_lshl_add_u64 v[214:215], s[42:43], 0, v[134:135]
	s_add_i32 m0, s62, 0x2000
	s_nop 0
	global_load_lds_dwordx4 v[214:215], off
	v_lshl_add_u64 v[214:215], s[28:29], 0, v[128:129]
	s_mov_b32 m0, s39
	s_nop 0
	global_load_lds_dwordx4 v[214:215], off
	s_mov_b32 m0, s40
	s_nop 0
	global_load_lds_dwordx4 v[216:217], off
	s_waitcnt vmcnt(8)
	s_waitcnt lgkmcnt(0)
	s_barrier
	s_setprio 0
	s_waitcnt lgkmcnt(0)
	v_mfma_f32_16x16x32_bf16 v[60:63], v[140:143], v[178:181], v[60:63]
	v_mfma_f32_16x16x32_bf16 v[56:59], v[154:157], v[178:181], v[56:59]
	v_mfma_f32_16x16x32_bf16 v[52:55], v[140:143], v[186:189], v[52:55]
	v_mfma_f32_16x16x32_bf16 v[44:47], v[154:157], v[186:189], v[44:47]
	v_mfma_f32_16x16x32_bf16 v[36:39], v[140:143], v[194:197], v[36:39]
	v_mfma_f32_16x16x32_bf16 v[28:31], v[154:157], v[194:197], v[28:31]
	v_mfma_f32_16x16x32_bf16 v[20:23], v[140:143], v[202:205], v[20:23]
	v_mfma_f32_16x16x32_bf16 v[12:15], v[154:157], v[202:205], v[12:15]
	v_mfma_f32_16x16x32_bf16 v[60:63], v[150:153], v[182:185], v[60:63]
	v_mfma_f32_16x16x32_bf16 v[56:59], v[158:161], v[182:185], v[56:59]
	v_mfma_f32_16x16x32_bf16 v[52:55], v[150:153], v[190:193], v[52:55]
	v_mfma_f32_16x16x32_bf16 v[44:47], v[158:161], v[190:193], v[44:47]
	v_mfma_f32_16x16x32_bf16 v[36:39], v[150:153], v[198:201], v[36:39]
	v_mfma_f32_16x16x32_bf16 v[28:31], v[158:161], v[198:201], v[28:31]
	v_mfma_f32_16x16x32_bf16 v[20:23], v[150:153], v[206:209], v[20:23]
	v_mfma_f32_16x16x32_bf16 v[12:15], v[158:161], v[206:209], v[12:15]
	v_mfma_f32_16x16x32_bf16 v[48:51], v[162:165], v[178:181], v[48:51]
	v_mfma_f32_16x16x32_bf16 v[40:43], v[170:173], v[178:181], v[40:43]
	v_mfma_f32_16x16x32_bf16 v[32:35], v[162:165], v[186:189], v[32:35]
	v_mfma_f32_16x16x32_bf16 v[24:27], v[170:173], v[186:189], v[24:27]
	v_mfma_f32_16x16x32_bf16 v[16:19], v[162:165], v[194:197], v[16:19]
	v_mfma_f32_16x16x32_bf16 v[8:11], v[170:173], v[194:197], v[8:11]
	v_mfma_f32_16x16x32_bf16 v[4:7], v[162:165], v[202:205], v[4:7]
	v_mfma_f32_16x16x32_bf16 v[0:3], v[170:173], v[202:205], v[0:3]
	v_mfma_f32_16x16x32_bf16 v[48:51], v[166:169], v[182:185], v[48:51]
	v_mfma_f32_16x16x32_bf16 v[40:43], v[174:177], v[182:185], v[40:43]
	v_mfma_f32_16x16x32_bf16 v[32:35], v[166:169], v[190:193], v[32:35]
	v_mfma_f32_16x16x32_bf16 v[24:27], v[174:177], v[190:193], v[24:27]
	v_mfma_f32_16x16x32_bf16 v[16:19], v[166:169], v[198:201], v[16:19]
	v_mfma_f32_16x16x32_bf16 v[8:11], v[174:177], v[198:201], v[8:11]
	v_mfma_f32_16x16x32_bf16 v[4:7], v[166:169], v[206:209], v[4:7]
	v_mfma_f32_16x16x32_bf16 v[0:3], v[174:177], v[206:209], v[0:3]
	s_setprio 3
	s_barrier
	s_add_i32 s42, 0, 0x18000
	s_add_i32 s43, 0, 0x1c000
	v_add_u32_e32 v158, s42, v145
	v_add_u32_e32 v174, s43, v145
	ds_read_b128 v[140:143], v158
	ds_read_b128 v[150:153], v158 offset:1024
	ds_read_b128 v[154:157], v158 offset:2048
	ds_read_b128 v[158:161], v158 offset:3072
	ds_read_b128 v[162:165], v174
	ds_read_b128 v[166:169], v174 offset:1024
	ds_read_b128 v[170:173], v174 offset:2048
	ds_read_b128 v[174:177], v174 offset:3072
	s_add_u32 s28, s28, 0x160000
	s_addc_u32 s29, s29, 0
	s_mov_b32 m0, s41
	v_lshl_add_u64 v[218:219], s[28:29], 0, v[128:129]
	ds_read_b128 v[178:181], v149 offset:32768
	ds_read_b128 v[182:185], v149 offset:33792
	ds_read_b128 v[186:189], v149 offset:34816
	ds_read_b128 v[190:193], v149 offset:35840
	ds_read_b128 v[194:197], v149 offset:36864
	ds_read_b128 v[198:201], v149 offset:37888
	ds_read_b128 v[202:205], v149 offset:38912
	ds_read_b128 v[206:209], v149 offset:39936
	global_load_lds_dwordx4 v[218:219], off
	v_lshl_add_u64 v[218:219], s[28:29], 0, v[132:133]
	s_mov_b32 m0, s44
	s_nop 0
	global_load_lds_dwordx4 v[218:219], off
	s_waitcnt vmcnt(8)
	s_waitcnt lgkmcnt(0)
	s_barrier
	s_setprio 0
	s_waitcnt lgkmcnt(0)
	v_mfma_f32_16x16x32_bf16 v[124:127], v[140:143], v[178:181], v[124:127]
	v_mfma_f32_16x16x32_bf16 v[120:123], v[154:157], v[178:181], v[120:123]
	v_mfma_f32_16x16x32_bf16 v[116:119], v[140:143], v[186:189], v[116:119]
	v_mfma_f32_16x16x32_bf16 v[108:111], v[154:157], v[186:189], v[108:111]
	v_mfma_f32_16x16x32_bf16 v[100:103], v[140:143], v[194:197], v[100:103]
	v_mfma_f32_16x16x32_bf16 v[92:95], v[154:157], v[194:197], v[92:95]
	v_mfma_f32_16x16x32_bf16 v[84:87], v[140:143], v[202:205], v[84:87]
	v_mfma_f32_16x16x32_bf16 v[76:79], v[154:157], v[202:205], v[76:79]
	v_mfma_f32_16x16x32_bf16 v[124:127], v[150:153], v[182:185], v[124:127]
	v_mfma_f32_16x16x32_bf16 v[120:123], v[158:161], v[182:185], v[120:123]
	v_mfma_f32_16x16x32_bf16 v[116:119], v[150:153], v[190:193], v[116:119]
	v_mfma_f32_16x16x32_bf16 v[108:111], v[158:161], v[190:193], v[108:111]
	v_mfma_f32_16x16x32_bf16 v[100:103], v[150:153], v[198:201], v[100:103]
	v_mfma_f32_16x16x32_bf16 v[92:95], v[158:161], v[198:201], v[92:95]
	v_mfma_f32_16x16x32_bf16 v[84:87], v[150:153], v[206:209], v[84:87]
	v_mfma_f32_16x16x32_bf16 v[76:79], v[158:161], v[206:209], v[76:79]
	v_mfma_f32_16x16x32_bf16 v[112:115], v[162:165], v[178:181], v[112:115]
	v_mfma_f32_16x16x32_bf16 v[104:107], v[170:173], v[178:181], v[104:107]
	v_mfma_f32_16x16x32_bf16 v[96:99], v[162:165], v[186:189], v[96:99]
	v_mfma_f32_16x16x32_bf16 v[88:91], v[170:173], v[186:189], v[88:91]
	v_mfma_f32_16x16x32_bf16 v[80:83], v[162:165], v[194:197], v[80:83]
	v_mfma_f32_16x16x32_bf16 v[72:75], v[170:173], v[194:197], v[72:75]
	v_mfma_f32_16x16x32_bf16 v[68:71], v[162:165], v[202:205], v[68:71]
	v_mfma_f32_16x16x32_bf16 v[64:67], v[170:173], v[202:205], v[64:67]
	v_mfma_f32_16x16x32_bf16 v[112:115], v[166:169], v[182:185], v[112:115]
	v_mfma_f32_16x16x32_bf16 v[104:107], v[174:177], v[182:185], v[104:107]
	v_mfma_f32_16x16x32_bf16 v[96:99], v[166:169], v[190:193], v[96:99]
	v_mfma_f32_16x16x32_bf16 v[88:91], v[174:177], v[190:193], v[88:91]
	v_mfma_f32_16x16x32_bf16 v[80:83], v[166:169], v[198:201], v[80:83]
	v_mfma_f32_16x16x32_bf16 v[72:75], v[174:177], v[198:201], v[72:75]
	v_mfma_f32_16x16x32_bf16 v[68:71], v[166:169], v[206:209], v[68:71]
	v_mfma_f32_16x16x32_bf16 v[64:67], v[174:177], v[206:209], v[64:67]
	s_setprio 3
	s_barrier
	s_add_i32 s28, s42, s35
	v_lshl_add_u64 v[210:211], v[210:211], 0, s[16:17]
	s_mov_b32 m0, s28
	ds_read_b128 v[178:181], v149 offset:49152
	ds_read_b128 v[182:185], v149 offset:50176
	ds_read_b128 v[186:189], v149 offset:51200
	ds_read_b128 v[190:193], v149 offset:52224
	ds_read_b128 v[194:197], v149 offset:53248
	ds_read_b128 v[198:201], v149 offset:54272
	ds_read_b128 v[202:205], v149 offset:55296
	ds_read_b128 v[206:209], v149 offset:56320
	global_load_lds_dwordx4 v[210:211], off
	s_add_i32 m0, s28, 0x2000
	s_add_u32 s26, s26, 0x160080
	v_lshl_add_u64 v[210:211], v[212:213], 0, s[16:17]
	s_addc_u32 s27, s27, 0
	s_add_i32 s28, s43, s35
	global_load_lds_dwordx4 v[210:211], off
	v_lshl_add_u64 v[210:211], s[26:27], 0, v[130:131]
	s_mov_b32 m0, s28
	s_nop 0
	global_load_lds_dwordx4 v[210:211], off
	v_lshl_add_u64 v[210:211], s[26:27], 0, v[134:135]
	s_add_i32 m0, s28, 0x2000
	s_nop 0
	global_load_lds_dwordx4 v[210:211], off
	v_lshl_add_u64 v[210:211], v[214:215], 0, s[16:17]
	s_mov_b32 m0, s46
	s_nop 0
	global_load_lds_dwordx4 v[210:211], off
	v_lshl_add_u64 v[210:211], v[216:217], 0, s[16:17]
	s_mov_b32 m0, s47
	s_nop 0
	global_load_lds_dwordx4 v[210:211], off
	s_waitcnt vmcnt(8)
	s_waitcnt lgkmcnt(0)
	s_barrier
	s_setprio 0
	s_waitcnt lgkmcnt(0)
	v_mfma_f32_16x16x32_bf16 v[60:63], v[140:143], v[178:181], v[60:63]
	v_mfma_f32_16x16x32_bf16 v[56:59], v[154:157], v[178:181], v[56:59]
	v_mfma_f32_16x16x32_bf16 v[52:55], v[140:143], v[186:189], v[52:55]
	v_mfma_f32_16x16x32_bf16 v[44:47], v[154:157], v[186:189], v[44:47]
	v_mfma_f32_16x16x32_bf16 v[36:39], v[140:143], v[194:197], v[36:39]
	v_mfma_f32_16x16x32_bf16 v[28:31], v[154:157], v[194:197], v[28:31]
	v_mfma_f32_16x16x32_bf16 v[20:23], v[140:143], v[202:205], v[20:23]
	v_mfma_f32_16x16x32_bf16 v[12:15], v[154:157], v[202:205], v[12:15]
	v_mfma_f32_16x16x32_bf16 v[60:63], v[150:153], v[182:185], v[60:63]
	v_mfma_f32_16x16x32_bf16 v[56:59], v[158:161], v[182:185], v[56:59]
	v_mfma_f32_16x16x32_bf16 v[52:55], v[150:153], v[190:193], v[52:55]
	v_mfma_f32_16x16x32_bf16 v[44:47], v[158:161], v[190:193], v[44:47]
	v_mfma_f32_16x16x32_bf16 v[36:39], v[150:153], v[198:201], v[36:39]
	v_mfma_f32_16x16x32_bf16 v[28:31], v[158:161], v[198:201], v[28:31]
	v_mfma_f32_16x16x32_bf16 v[20:23], v[150:153], v[206:209], v[20:23]
	v_mfma_f32_16x16x32_bf16 v[12:15], v[158:161], v[206:209], v[12:15]
	v_mfma_f32_16x16x32_bf16 v[48:51], v[162:165], v[178:181], v[48:51]
	v_mfma_f32_16x16x32_bf16 v[40:43], v[170:173], v[178:181], v[40:43]
	v_mfma_f32_16x16x32_bf16 v[32:35], v[162:165], v[186:189], v[32:35]
	v_mfma_f32_16x16x32_bf16 v[24:27], v[170:173], v[186:189], v[24:27]
	v_mfma_f32_16x16x32_bf16 v[16:19], v[162:165], v[194:197], v[16:19]
	v_mfma_f32_16x16x32_bf16 v[8:11], v[170:173], v[194:197], v[8:11]
	v_mfma_f32_16x16x32_bf16 v[4:7], v[162:165], v[202:205], v[4:7]
	v_mfma_f32_16x16x32_bf16 v[0:3], v[170:173], v[202:205], v[0:3]
	v_mfma_f32_16x16x32_bf16 v[48:51], v[166:169], v[182:185], v[48:51]
	v_mfma_f32_16x16x32_bf16 v[40:43], v[174:177], v[182:185], v[40:43]
	v_mfma_f32_16x16x32_bf16 v[32:35], v[166:169], v[190:193], v[32:35]
	v_mfma_f32_16x16x32_bf16 v[24:27], v[174:177], v[190:193], v[24:27]
	v_mfma_f32_16x16x32_bf16 v[16:19], v[166:169], v[198:201], v[16:19]
	v_mfma_f32_16x16x32_bf16 v[8:11], v[174:177], v[198:201], v[8:11]
	v_mfma_f32_16x16x32_bf16 v[4:7], v[166:169], v[206:209], v[4:7]
	v_mfma_f32_16x16x32_bf16 v[0:3], v[174:177], v[206:209], v[0:3]
	s_setprio 3
	s_barrier
	s_add_i32 s26, s61, 2
	s_cmpk_gt_u32 s61, 0x55
	s_mov_b32 s61, s26
	s_cbranch_scc0 .LBB0_2466
	s_and_b64 vcc, exec, s[18:19]
	s_cbranch_vccz .LBB0_2469
	s_barrier
